# GEMM1 epilogue layout: z and v bodies of row groups 1..7 separated and made adjacent per kind, block heads next to the spines (on top of the u-block regrouping)
# speedup vs baseline: 1.0070x; 1.0070x over previous
; __device__ __forceinline__ float gelu_tanh(float x) { const float u = 1.5957691216f * (x + 0.044715f * x * x * x); return x * __builtin_amdgcn_rcpf(1.f + __expf(-u)); }
; __device__ __forceinline__ void st_bf16x8(bf16_t* p, const f32x4 a, const f32x4 b) { uint4 o; o.x = cvt_pk_bf16(a[0], a[1]); o.y = cvt_pk_bf16(a[2], a[3]); o.z = cvt_pk_bf16(b[0], b[1]); o.w = cvt_pk_bf16(b[2], b[3]); *(uint4*)p = o; }
;     __device__ __forceinline__ void row(const f32x4 (&a)[2][2], int row, int pn, int wc, int fq) const {
;     ...
;         } else if (pn < 4) {
;             const int head = (pn - 2) * 4 + wc;
;             f32x4 g[2][2]; float ss = 0.f;
; #pragma unroll
;             for (int bj = 0; bj < 2; ++bj)
; #pragma unroll
;                 for (int n = 0; n < 2; ++n)
; #pragma unroll
;                     for (int j = 0; j < 4; ++j) { const float t = gelu_tanh(a[bj][n][j]); g[bj][n][j] = t; ss += t * t; }
;             ss += __shfl_xor(ss, 16); ss += __shfl_xor(ss, 32);
;             const float rs = rsqrtf(ss * (1.f / 64.f) + EPS);
; #pragma unroll
;             for (int bj = 0; bj < 2; ++bj) { const int d = head * 64 + bj * 32 + 8 * fq;
;                 const f32x4 v0 = g[bj][0] * rs * *(const f32x4*)(g_v + d), v1 = g[bj][1] * rs * *(const f32x4*)(g_v + d + 4);
;                 st_bf16x8(pV + (size_t)row * 512 + d, v0, v1);
;                 if (row >= NP && row < NTOK) { float* o = out + O_VS + (size_t)(row - NP) * 512 + d; *(f32x4*)o = v0; *(f32x4*)(o + 4) = v1; } }
;         } else {
.LBB0_236:
	s_and_b64 vcc, exec, s[6:7]
	s_cbranch_vccnz .Lv_1
	s_branch .Lz_1

.LBB0_282:
	v_cvt_pk_bf16_f32 v68, v68, v69
	v_cvt_pk_bf16_f32 v69, v70, v71
	v_cvt_pk_bf16_f32 v70, v64, v65
	s_nop 0
	v_cvt_pk_bf16_f32 v71, v66, v67
	global_store_dwordx4 v[80:81], v[68:71], off offset:256
	s_branch .LBB0_283
.LBB0_283:
	v_add_u32_e32 v72, 0x80, v156
	v_and_b32_e32 v64, 0xffffff80, v72
	s_movk_i32 s0, 0x4000
	v_cmp_eq_u32_e64 s[10:11], s0, v64
	s_and_b64 vcc, exec, s[8:9]
	s_mov_b64 s[0:1], -1
	s_cbranch_vccz .LBB0_291
	s_andn2_b64 vcc, exec, s[0:1]
	s_cbranch_vccz .LBB0_302

; __device__ __forceinline__ void st_bf16x8(bf16_t* p, const f32x4 a, const f32x4 b) { uint4 o; o.x = cvt_pk_bf16(a[0], a[1]); o.y = cvt_pk_bf16(a[2], a[3]); o.z = cvt_pk_bf16(b[0], b[1]); o.w = cvt_pk_bf16(b[2], b[3]); *(uint4*)p = o; }
;     __device__ __forceinline__ void row(const f32x4 (&a)[2][2], int row, int pn, int wc, int fq) const {
;     ...
;         } else {
;             const int c = (pn - 6) * 128 + wc * 32 + 8 * fq;
;             const f32x4 z0 = a[0][0] * a[1][0], z1 = a[0][1] * a[1][1];
;             st_bf16x8(pZ + (size_t)row * 512 + c, z0, z1);
;             float* o = nullptr;
;             if (row < NP) { const int t = row & 2047; if (t >= 2046) o = out + O_CONVP + (size_t)((row >> 11) * 2 + (t - 2046)) * 512 + c; }
;             else if (row < NTOK) o = out + O_CONVS + (size_t)((row - NP) * 2 + 1) * 512 + c;
;             if (o) { *(f32x4*)o = z0; *(f32x4*)(o + 4) = z1; }
;         }
.Lz_1:
	v_ashrrev_i32_e32 v121, 31, v120
	v_lshlrev_b64 v[122:123], 10, v[120:121]
	s_cmpk_lt_u32 s73, 0x4080
	v_lshl_add_u64 v[122:123], s[50:51], 0, v[122:123]
	v_cmp_lt_i32_e32 vcc, s12, v120
	s_cselect_b64 s[0:1], -1, 0
	v_pk_mul_f32 v[114:115], v[110:111], v[102:103]
	v_pk_mul_f32 v[112:113], v[108:109], v[100:101]
	v_pk_mul_f32 v[118:119], v[106:107], v[98:99]
	v_pk_mul_f32 v[116:117], v[104:105], v[96:97]
	v_lshl_add_u64 v[126:127], v[154:155], 1, v[122:123]
	s_and_b64 s[82:83], vcc, s[0:1]
	v_cvt_pk_bf16_f32 v122, v112, v113
	v_cvt_pk_bf16_f32 v123, v114, v115
	v_cvt_pk_bf16_f32 v124, v116, v117
	v_cvt_pk_bf16_f32 v125, v118, v119
	global_store_dwordx4 v[126:127], v[122:125], off
	s_and_saveexec_b64 s[0:1], s[82:83]
	s_cbranch_execz .LBB0_239
	v_lshl_add_u32 v122, v120, 1, v189
	v_mov_b32_e32 v123, v141
	v_lshlrev_b64 v[122:123], 11, v[122:123]
	v_lshl_add_u64 v[122:123], s[66:67], 0, v[122:123]
	v_lshl_add_u64 v[122:123], v[154:155], 2, v[122:123]
	global_store_dwordx4 v[122:123], v[112:115], off
	global_store_dwordx4 v[122:123], v[116:119], off offset:16
.LBB0_239:
	s_or_b64 exec, exec, s[0:1]
	s_mov_b64 s[0:1], 0
.LBB0_240:
	s_andn2_b64 vcc, exec, s[0:1]
	s_cbranch_vccnz .LBB0_245
	s_branch .Lv_1
.LBB0_245:
	s_cbranch_execnz .LBB0_232
	s_branch .LBB0_246
.Lz_2:
	v_ashrrev_i32_e32 v105, 31, v104
	v_lshlrev_b64 v[106:107], 10, v[104:105]
	s_cmpk_lt_u32 s73, 0x4080
	v_lshl_add_u64 v[106:107], s[50:51], 0, v[106:107]
	v_cmp_lt_i32_e32 vcc, s12, v104
	s_cselect_b64 s[0:1], -1, 0
	v_pk_mul_f32 v[98:99], v[94:95], v[86:87]
	v_pk_mul_f32 v[96:97], v[92:93], v[84:85]
	v_pk_mul_f32 v[102:103], v[90:91], v[82:83]
	v_pk_mul_f32 v[100:101], v[88:89], v[80:81]
	v_lshl_add_u64 v[110:111], v[154:155], 1, v[106:107]
	s_and_b64 s[82:83], vcc, s[0:1]
	v_cvt_pk_bf16_f32 v106, v96, v97
	v_cvt_pk_bf16_f32 v107, v98, v99
	v_cvt_pk_bf16_f32 v108, v100, v101
	v_cvt_pk_bf16_f32 v109, v102, v103
	global_store_dwordx4 v[110:111], v[106:109], off
	s_and_saveexec_b64 s[0:1], s[82:83]
	s_cbranch_execz .LBB0_254
	v_lshl_add_u32 v106, v104, 1, v189
	v_mov_b32_e32 v107, v141
	v_lshlrev_b64 v[106:107], 11, v[106:107]
	v_lshl_add_u64 v[106:107], s[66:67], 0, v[106:107]
	v_lshl_add_u64 v[106:107], v[154:155], 2, v[106:107]
	global_store_dwordx4 v[106:107], v[96:99], off
	global_store_dwordx4 v[106:107], v[100:103], off offset:16
.LBB0_254:
	s_or_b64 exec, exec, s[0:1]
	s_mov_b64 s[0:1], 0
.LBB0_255:
	s_andn2_b64 vcc, exec, s[0:1]
	s_cbranch_vccnz .LBB0_260
	s_branch .Lv_2
.LBB0_260:
	s_cbranch_execnz .LBB0_234
	s_branch .LBB0_261
.Lz_3:
	v_ashrrev_i32_e32 v89, 31, v88
	v_lshlrev_b64 v[90:91], 10, v[88:89]
	v_lshl_add_u64 v[90:91], s[50:51], 0, v[90:91]
	v_pk_mul_f32 v[82:83], v[78:79], v[70:71]
	v_pk_mul_f32 v[80:81], v[76:77], v[68:69]
	v_pk_mul_f32 v[86:87], v[74:75], v[66:67]
	v_pk_mul_f32 v[84:85], v[72:73], v[64:65]
	v_lshl_add_u64 v[94:95], v[154:155], 1, v[90:91]
	v_cvt_pk_bf16_f32 v90, v80, v81
	v_cvt_pk_bf16_f32 v91, v82, v83
	v_cmp_lt_i32_e32 vcc, s12, v88
	v_cvt_pk_bf16_f32 v92, v84, v85
	v_cvt_pk_bf16_f32 v93, v86, v87
	global_store_dwordx4 v[94:95], v[90:93], off
	s_and_saveexec_b64 s[82:83], vcc
	s_xor_b64 s[82:83], exec, s[82:83]
	s_cbranch_execnz .LBB0_356
	s_or_saveexec_b64 s[82:83], s[82:83]
	v_mov_b64_e32 v[92:93], 0x4088000
	s_xor_b64 exec, exec, s[82:83]
	s_cbranch_execnz .LBB0_357

;     __device__ __forceinline__ void row(const f32x4 (&a)[2][2], int row, int pn, int wc, int fq) const {
;     ...
;         } else if (pn < 4) {
.LBB0_272:
	s_and_b64 vcc, exec, s[0:1]
	s_cbranch_vccz .LBB0_277
	s_branch .Lv_3

; __device__ __forceinline__ void st_bf16x8(bf16_t* p, const f32x4 a, const f32x4 b) { uint4 o; o.x = cvt_pk_bf16(a[0], a[1]); o.y = cvt_pk_bf16(a[2], a[3]); o.z = cvt_pk_bf16(b[0], b[1]); o.w = cvt_pk_bf16(b[2], b[3]); *(uint4*)p = o; }
;     __device__ __forceinline__ void row(const f32x4 (&a)[2][2], int row, int pn, int wc, int fq) const {
;     ...
;         } else {
;             const int c = (pn - 6) * 128 + wc * 32 + 8 * fq;
;             const f32x4 z0 = a[0][0] * a[1][0], z1 = a[0][1] * a[1][1];
;             st_bf16x8(pZ + (size_t)row * 512 + c, z0, z1);
;             float* o = nullptr;
;             if (row < NP) { const int t = row & 2047; if (t >= 2046) o = out + O_CONVP + (size_t)((row >> 11) * 2 + (t - 2046)) * 512 + c; }
;             else if (row < NTOK) o = out + O_CONVS + (size_t)((row - NP) * 2 + 1) * 512 + c;
;             if (o) { *(f32x4*)o = z0; *(f32x4*)(o + 4) = z1; }
;         }
.Lz_4:
	v_ashrrev_i32_e32 v73, 31, v72
	v_lshlrev_b64 v[74:75], 10, v[72:73]
	v_lshl_add_u64 v[74:75], s[50:51], 0, v[74:75]
	v_pk_mul_f32 v[66:67], v[62:63], v[54:55]
	v_pk_mul_f32 v[64:65], v[60:61], v[52:53]
	v_lshl_add_u64 v[78:79], v[154:155], 1, v[74:75]
	v_cvt_pk_bf16_f32 v74, v64, v65
	v_cvt_pk_bf16_f32 v75, v66, v67
	v_pk_mul_f32 v[70:71], v[58:59], v[50:51]
	v_pk_mul_f32 v[68:69], v[56:57], v[48:49]
	v_cvt_pk_bf16_f32 v77, v70, v71
	s_mov_b64 s[82:83], 0x88800
	v_cvt_pk_bf16_f32 v76, v68, v69
	global_store_dwordx4 v[78:79], v[74:77], off
	s_cmpk_eq_i32 s75, 0x3f80
	s_cselect_b64 s[0:1], -1, 0
	v_lshlrev_b32_e32 v74, 12, v72
	v_mov_b32_e32 v75, v141
	v_lshl_add_u64 v[74:75], s[56:57], 0, v[74:75]
	v_lshl_add_u64 v[74:75], v[74:75], 0, s[82:83]
	v_cmp_ne_u64_e32 vcc, 0, v[74:75]
	s_and_b64 s[82:83], s[0:1], vcc
	s_and_saveexec_b64 s[0:1], s[82:83]
	s_cbranch_execz .LBB0_294
	v_lshl_add_u64 v[74:75], v[154:155], 2, v[74:75]
	global_store_dwordx4 v[74:75], v[64:67], off
	global_store_dwordx4 v[74:75], v[68:71], off offset:16
.LBB0_294:
	s_or_b64 exec, exec, s[0:1]
	s_mov_b64 s[0:1], 0
.LBB0_295:
	s_andn2_b64 vcc, exec, s[0:1]
	s_cbranch_vccnz .LBB0_301
	s_branch .Lv_4
.LBB0_301:
	s_cbranch_execnz .LBB0_285
	s_branch .LBB0_302
.Lz_5:
	v_ashrrev_i32_e32 v57, 31, v56
	v_lshlrev_b64 v[58:59], 10, v[56:57]
	v_lshl_add_u64 v[58:59], s[50:51], 0, v[58:59]
	s_add_i32 s0, s73, 0xffffc010
	v_pk_mul_f32 v[50:51], v[46:47], v[38:39]
	v_pk_mul_f32 v[48:49], v[44:45], v[36:37]
	v_pk_mul_f32 v[54:55], v[42:43], v[34:35]
	v_pk_mul_f32 v[52:53], v[40:41], v[32:33]
	v_lshl_add_u64 v[62:63], v[154:155], 1, v[58:59]
	s_cmp_lt_u32 s0, 0xffffff80
	v_cvt_pk_bf16_f32 v58, v48, v49
	v_cvt_pk_bf16_f32 v59, v50, v51
	v_cvt_pk_bf16_f32 v60, v52, v53
	v_cvt_pk_bf16_f32 v61, v54, v55
	global_store_dwordx4 v[62:63], v[58:61], off
	s_cbranch_scc1 .LBB0_310
	s_nop 0
	v_lshl_add_u32 v58, v56, 1, v189
	v_mov_b32_e32 v59, v141
	v_lshlrev_b64 v[58:59], 11, v[58:59]
	v_lshl_add_u64 v[58:59], s[66:67], 0, v[58:59]
	v_lshl_add_u64 v[58:59], v[154:155], 2, v[58:59]
	global_store_dwordx4 v[58:59], v[48:51], off
	global_store_dwordx4 v[58:59], v[52:55], off offset:16
.LBB0_310:
	s_mov_b64 s[0:1], 0
.LBB0_311:
	s_andn2_b64 vcc, exec, s[0:1]
	s_cbranch_vccnz .LBB0_317
	s_branch .Lv_5
.LBB0_317:
	s_cbranch_execnz .LBB0_287
	s_branch .LBB0_318
.Lz_6:
	v_ashrrev_i32_e32 v41, 31, v40
	v_lshlrev_b64 v[42:43], 10, v[40:41]
	v_lshl_add_u64 v[42:43], s[50:51], 0, v[42:43]
	s_addk_i32 s73, 0xc020
	v_pk_mul_f32 v[34:35], v[30:31], v[22:23]
	v_pk_mul_f32 v[32:33], v[28:29], v[20:21]
	v_pk_mul_f32 v[38:39], v[26:27], v[18:19]
	v_pk_mul_f32 v[36:37], v[24:25], v[16:17]
	v_lshl_add_u64 v[46:47], v[154:155], 1, v[42:43]
	s_cmp_lt_u32 s73, 0xffffff80
	v_cvt_pk_bf16_f32 v42, v32, v33
	v_cvt_pk_bf16_f32 v43, v34, v35
	v_cvt_pk_bf16_f32 v44, v36, v37
	v_cvt_pk_bf16_f32 v45, v38, v39
	global_store_dwordx4 v[46:47], v[42:45], off
	s_cbranch_scc1 .LBB0_326
	s_nop 0
	v_lshl_add_u32 v42, v40, 1, v189
	v_mov_b32_e32 v43, v141
	v_lshlrev_b64 v[42:43], 11, v[42:43]
	v_lshl_add_u64 v[42:43], s[66:67], 0, v[42:43]
	v_lshl_add_u64 v[42:43], v[154:155], 2, v[42:43]
	global_store_dwordx4 v[42:43], v[32:35], off
	global_store_dwordx4 v[42:43], v[36:39], off offset:16
.LBB0_326:
	s_mov_b64 s[0:1], 0
.LBB0_327:
	s_andn2_b64 vcc, exec, s[0:1]
	s_cbranch_vccnz .LBB0_333
	s_branch .Lv_6
.LBB0_333:
	s_cbranch_execnz .LBB0_289
	s_branch .LBB0_334
.Lz_7:
	v_ashrrev_i32_e32 v25, 31, v24
	v_lshlrev_b64 v[26:27], 10, v[24:25]
	v_lshl_add_u64 v[26:27], s[50:51], 0, v[26:27]
	s_movk_i32 s0, 0x3f4f
	v_pk_mul_f32 v[18:19], v[14:15], v[6:7]
	v_pk_mul_f32 v[16:17], v[12:13], v[4:5]
	v_pk_mul_f32 v[22:23], v[10:11], v[2:3]
	v_pk_mul_f32 v[20:21], v[8:9], v[0:1]
	v_lshl_add_u64 v[30:31], v[154:155], 1, v[26:27]
	v_cvt_pk_bf16_f32 v26, v16, v17
	v_cvt_pk_bf16_f32 v27, v18, v19
	v_cmp_lt_i32_e32 vcc, s0, v156
	v_cvt_pk_bf16_f32 v28, v20, v21
	v_cvt_pk_bf16_f32 v29, v22, v23
	global_store_dwordx4 v[30:31], v[26:29], off
	s_and_saveexec_b64 s[6:7], vcc
	s_xor_b64 s[6:7], exec, s[6:7]
	s_cbranch_execnz .LBB0_358
	s_or_saveexec_b64 s[6:7], s[6:7]
	v_mov_b64_e32 v[28:29], 0x4088000
	s_xor_b64 exec, exec, s[6:7]
	s_cbranch_execnz .LBB0_359

; __device__ __forceinline__ float gelu_tanh(float x) { const float u = 1.5957691216f * (x + 0.044715f * x * x * x); return x * __builtin_amdgcn_rcpf(1.f + __expf(-u)); }
; __device__ __forceinline__ void st_bf16x8(bf16_t* p, const f32x4 a, const f32x4 b) { uint4 o; o.x = cvt_pk_bf16(a[0], a[1]); o.y = cvt_pk_bf16(a[2], a[3]); o.z = cvt_pk_bf16(b[0], b[1]); o.w = cvt_pk_bf16(b[2], b[3]); *(uint4*)p = o; }
;     __device__ __forceinline__ void row(const f32x4 (&a)[2][2], int row, int pn, int wc, int fq) const {
;     ...
;         } else if (pn < 4) {
;             const int head = (pn - 2) * 4 + wc;
;             f32x4 g[2][2]; float ss = 0.f;
; #pragma unroll
;             for (int bj = 0; bj < 2; ++bj)
; #pragma unroll
;                 for (int n = 0; n < 2; ++n)
; #pragma unroll
;                     for (int j = 0; j < 4; ++j) { const float t = gelu_tanh(a[bj][n][j]); g[bj][n][j] = t; ss += t * t; }
;             ss += __shfl_xor(ss, 16); ss += __shfl_xor(ss, 32);
;             const float rs = rsqrtf(ss * (1.f / 64.f) + EPS);
; #pragma unroll
;             for (int bj = 0; bj < 2; ++bj) { const int d = head * 64 + bj * 32 + 8 * fq;
;                 const f32x4 v0 = g[bj][0] * rs * *(const f32x4*)(g_v + d), v1 = g[bj][1] * rs * *(const f32x4*)(g_v + d + 4);
;                 st_bf16x8(pV + (size_t)row * 512 + d, v0, v1);
;                 if (row >= NP && row < NTOK) { float* o = out + O_VS + (size_t)(row - NP) * 512 + d; *(f32x4*)o = v0; *(f32x4*)(o + 4) = v1; } }
.Lv_1:
	s_andn2_b64 vcc, exec, s[0:1]
	v_mov_b32_e32 v190, 0x3d372713
	v_mov_b32_e32 v192, 0xbfcc422a
	v_mov_b32_e32 v194, 0x3fb8aa3b
	v_pk_mul_f32 v[112:113], v[108:109], v[190:191] op_sel_hi:[1,0]
	v_pk_mul_f32 v[116:117], v[110:111], v[190:191] op_sel_hi:[1,0]
	v_pk_mul_f32 v[122:123], v[104:105], v[190:191] op_sel_hi:[1,0]
	v_pk_mul_f32 v[124:125], v[106:107], v[190:191] op_sel_hi:[1,0]
	v_pk_mul_f32 v[126:127], v[100:101], v[190:191] op_sel_hi:[1,0]
	v_pk_mul_f32 v[128:129], v[102:103], v[190:191] op_sel_hi:[1,0]
	v_pk_mul_f32 v[130:131], v[96:97], v[190:191] op_sel_hi:[1,0]
	v_pk_mul_f32 v[132:133], v[98:99], v[190:191] op_sel_hi:[1,0]
	v_pk_mul_f32 v[112:113], v[108:109], v[112:113]
	v_pk_mul_f32 v[116:117], v[110:111], v[116:117]
	v_pk_mul_f32 v[122:123], v[104:105], v[122:123]
	v_pk_mul_f32 v[124:125], v[106:107], v[124:125]
	v_pk_mul_f32 v[126:127], v[100:101], v[126:127]
	v_pk_mul_f32 v[128:129], v[102:103], v[128:129]
	v_pk_mul_f32 v[130:131], v[96:97], v[130:131]
	v_pk_mul_f32 v[132:133], v[98:99], v[132:133]
	v_pk_fma_f32 v[112:113], v[108:109], v[112:113], v[108:109]
	v_pk_fma_f32 v[116:117], v[110:111], v[116:117], v[110:111]
	v_pk_fma_f32 v[122:123], v[104:105], v[122:123], v[104:105]
	v_pk_fma_f32 v[124:125], v[106:107], v[124:125], v[106:107]
	v_pk_fma_f32 v[126:127], v[100:101], v[126:127], v[100:101]
	v_pk_fma_f32 v[128:129], v[102:103], v[128:129], v[102:103]
	v_pk_fma_f32 v[130:131], v[96:97], v[130:131], v[96:97]
	v_pk_fma_f32 v[132:133], v[98:99], v[132:133], v[98:99]
	v_pk_mul_f32 v[112:113], v[112:113], v[192:193] op_sel_hi:[1,0]
	v_pk_mul_f32 v[116:117], v[116:117], v[192:193] op_sel_hi:[1,0]
	v_pk_mul_f32 v[122:123], v[122:123], v[192:193] op_sel_hi:[1,0]
	v_pk_mul_f32 v[124:125], v[124:125], v[192:193] op_sel_hi:[1,0]
	v_pk_mul_f32 v[126:127], v[126:127], v[192:193] op_sel_hi:[1,0]
	v_pk_mul_f32 v[128:129], v[128:129], v[192:193] op_sel_hi:[1,0]
	v_pk_mul_f32 v[130:131], v[130:131], v[192:193] op_sel_hi:[1,0]
	v_pk_mul_f32 v[132:133], v[132:133], v[192:193] op_sel_hi:[1,0]
	v_pk_mul_f32 v[112:113], v[112:113], v[194:195] op_sel_hi:[1,0]
	v_pk_mul_f32 v[116:117], v[116:117], v[194:195] op_sel_hi:[1,0]
	v_pk_mul_f32 v[122:123], v[122:123], v[194:195] op_sel_hi:[1,0]
	v_pk_mul_f32 v[124:125], v[124:125], v[194:195] op_sel_hi:[1,0]
	v_pk_mul_f32 v[126:127], v[126:127], v[194:195] op_sel_hi:[1,0]
	v_pk_mul_f32 v[128:129], v[128:129], v[194:195] op_sel_hi:[1,0]
	v_pk_mul_f32 v[130:131], v[130:131], v[194:195] op_sel_hi:[1,0]
	v_pk_mul_f32 v[132:133], v[132:133], v[194:195] op_sel_hi:[1,0]
	v_exp_f32_e32 v112, v112
	v_exp_f32_e32 v113, v113
	v_exp_f32_e32 v116, v116
	v_exp_f32_e32 v117, v117
	v_exp_f32_e32 v122, v122
	v_exp_f32_e32 v123, v123
	v_exp_f32_e32 v124, v124
	v_exp_f32_e32 v125, v125
	v_exp_f32_e32 v126, v126
	v_exp_f32_e32 v127, v127
	v_exp_f32_e32 v128, v128
	v_exp_f32_e32 v129, v129
	v_exp_f32_e32 v130, v130
	v_exp_f32_e32 v131, v131
	v_exp_f32_e32 v132, v132
	v_exp_f32_e32 v133, v133
	v_pk_add_f32 v[112:113], v[112:113], 1.0 op_sel_hi:[1,0]
	v_pk_add_f32 v[116:117], v[116:117], 1.0 op_sel_hi:[1,0]
	v_pk_add_f32 v[122:123], v[122:123], 1.0 op_sel_hi:[1,0]
	v_pk_add_f32 v[124:125], v[124:125], 1.0 op_sel_hi:[1,0]
	v_pk_add_f32 v[126:127], v[126:127], 1.0 op_sel_hi:[1,0]
	v_pk_add_f32 v[128:129], v[128:129], 1.0 op_sel_hi:[1,0]
	v_pk_add_f32 v[130:131], v[130:131], 1.0 op_sel_hi:[1,0]
	v_pk_add_f32 v[132:133], v[132:133], 1.0 op_sel_hi:[1,0]
	v_rcp_f32_e32 v112, v112
	v_rcp_f32_e32 v113, v113
	v_rcp_f32_e32 v116, v116
	v_rcp_f32_e32 v117, v117
	v_rcp_f32_e32 v122, v122
	v_rcp_f32_e32 v123, v123
	v_rcp_f32_e32 v124, v124
	v_rcp_f32_e32 v125, v125
	v_rcp_f32_e32 v126, v126
	v_rcp_f32_e32 v127, v127
	v_rcp_f32_e32 v128, v128
	v_rcp_f32_e32 v129, v129
	v_rcp_f32_e32 v130, v130
	v_rcp_f32_e32 v131, v131
	v_rcp_f32_e32 v132, v132
	v_rcp_f32_e32 v133, v133
	v_pk_mul_f32 v[112:113], v[108:109], v[112:113]
	v_pk_mul_f32 v[116:117], v[110:111], v[116:117]
	v_pk_mul_f32 v[122:123], v[104:105], v[122:123]
	v_pk_mul_f32 v[124:125], v[106:107], v[124:125]
	v_pk_mul_f32 v[126:127], v[100:101], v[126:127]
	v_pk_mul_f32 v[128:129], v[102:103], v[128:129]
	v_pk_mul_f32 v[130:131], v[96:97], v[130:131]
	v_pk_mul_f32 v[132:133], v[98:99], v[132:133]
	v_pk_mul_f32 v[114:115], v[112:113], v[112:113]
	v_pk_mul_f32 v[118:119], v[116:117], v[116:117]
	v_add_f32_e32 v114, v114, v115
	v_add_f32_e32 v114, v118, v114
	v_pk_mul_f32 v[134:135], v[122:123], v[122:123]
	v_add_f32_e32 v114, v119, v114
	v_add_f32_e32 v114, v134, v114
	v_pk_mul_f32 v[158:159], v[124:125], v[124:125]
	v_add_f32_e32 v114, v135, v114
	v_add_f32_e32 v114, v158, v114
	v_pk_mul_f32 v[160:161], v[126:127], v[126:127]
	v_add_f32_e32 v114, v159, v114
	v_add_f32_e32 v114, v114, v160
	v_pk_mul_f32 v[162:163], v[128:129], v[128:129]
	v_add_f32_e32 v114, v161, v114
	v_add_f32_e32 v114, v162, v114
	v_pk_mul_f32 v[164:165], v[130:131], v[130:131]
	v_add_f32_e32 v114, v163, v114
	v_add_f32_e32 v114, v164, v114
	v_pk_mul_f32 v[166:167], v[132:133], v[132:133]
	v_add_f32_e32 v114, v165, v114
	v_add_f32_e32 v114, v166, v114
	v_add_f32_e32 v114, v167, v114
	ds_bpermute_b32 v115, v229, v114
	v_lshl_add_u64 v[166:167], v[140:141], 2, s[18:19]
	v_ashrrev_i32_e32 v121, 31, v120
	v_lshlrev_b64 v[160:161], 10, v[120:121]
	v_lshlrev_b32_e32 v158, 9, v120
	s_waitcnt lgkmcnt(0)
	v_add_f32_e32 v114, v114, v115
	ds_bpermute_b32 v115, v230, v114
	v_mov_b32_e32 v159, v141
	v_cndmask_b32_e64 v121, 0, 1, s[10:11]
	v_cmp_ne_u32_e64 s[0:1], 1, v121
	s_waitcnt lgkmcnt(0)
	v_add_f32_e32 v114, v114, v115
	v_fmamk_f32 v114, v114, 0x3c800000, v188
	v_cmp_gt_f32_e32 vcc, s13, v114
	v_mul_f32_e32 v115, 0x4b800000, v114
	s_nop 0
	v_cndmask_b32_e32 v114, v114, v115, vcc
	v_rsq_f32_e32 v114, v114
	s_nop 0
	v_mul_f32_e32 v115, 0x45800000, v114
	v_cndmask_b32_e32 v134, v114, v115, vcc
	v_pk_mul_f32 v[162:163], v[112:113], v[134:135] op_sel_hi:[1,0]
	v_pk_mul_f32 v[164:165], v[116:117], v[134:135] op_sel_hi:[1,0]
	v_mov_b64_e32 v[112:113], v[208:209]
	v_mov_b64_e32 v[114:115], v[210:211]
	v_mov_b64_e32 v[116:117], v[204:205]
	v_mov_b64_e32 v[118:119], v[206:207]
	v_pk_mul_f32 v[122:123], v[122:123], v[134:135] op_sel_hi:[1,0]
	v_pk_mul_f32 v[124:125], v[124:125], v[134:135] op_sel_hi:[1,0]
	s_andn2_b64 vcc, exec, s[10:11]
	v_pk_mul_f32 v[112:113], v[112:113], v[122:123]
	v_lshl_add_u64 v[122:123], s[46:47], 0, v[160:161]
	v_pk_mul_f32 v[118:119], v[118:119], v[164:165]
	v_pk_mul_f32 v[116:117], v[116:117], v[162:163]
	v_pk_mul_f32 v[114:115], v[114:115], v[124:125]
	v_lshl_add_u64 v[122:123], v[140:141], 1, v[122:123]
	v_lshl_add_u64 v[124:125], v[158:159], 2, s[56:57]
	v_cvt_pk_bf16_f32 v160, v116, v117
	v_cvt_pk_bf16_f32 v161, v118, v119
	v_cvt_pk_bf16_f32 v162, v112, v113
	v_cvt_pk_bf16_f32 v163, v114, v115
	v_mov_b64_e32 v[196:197], v[160:161]
	v_mov_b64_e32 v[198:199], v[162:163]
	s_cbranch_vccnz .LBB0_243
; __device__ __forceinline__ void st_bf16x8(bf16_t* p, const f32x4 a, const f32x4 b) { uint4 o; o.x = cvt_pk_bf16(a[0], a[1]); o.y = cvt_pk_bf16(a[2], a[3]); o.z = cvt_pk_bf16(b[0], b[1]); o.w = cvt_pk_bf16(b[2], b[3]); *(uint4*)p = o; }
;     __device__ __forceinline__ void row(const f32x4 (&a)[2][2], int row, int pn, int wc, int fq) const {
;     ...
;                 const f32x4 v0 = g[bj][0] * rs * *(const f32x4*)(g_v + d), v1 = g[bj][1] * rs * *(const f32x4*)(g_v + d + 4);
;                 st_bf16x8(pV + (size_t)row * 512 + d, v0, v1);
;                 if (row >= NP && row < NTOK) { float* o = out + O_VS + (size_t)(row - NP) * 512 + d; *(f32x4*)o = v0; *(f32x4*)(o + 4) = v1; } }
	v_lshl_add_u64 v[158:159], v[140:141], 2, v[124:125]
	v_lshl_add_u64 v[160:161], v[158:159], 0, s[70:71]
	v_add_co_u32_e32 v158, vcc, 0x2108000, v158
	s_nop 1
	v_addc_co_u32_e32 v159, vcc, 0, v159, vcc
	global_store_dwordx4 v[158:159], v[116:119], off
	global_store_dwordx4 v[160:161], v[112:115], off offset:16

; __device__ __forceinline__ float gelu_tanh(float x) { const float u = 1.5957691216f * (x + 0.044715f * x * x * x); return x * __builtin_amdgcn_rcpf(1.f + __expf(-u)); }
; __device__ __forceinline__ void st_bf16x8(bf16_t* p, const f32x4 a, const f32x4 b) { uint4 o; o.x = cvt_pk_bf16(a[0], a[1]); o.y = cvt_pk_bf16(a[2], a[3]); o.z = cvt_pk_bf16(b[0], b[1]); o.w = cvt_pk_bf16(b[2], b[3]); *(uint4*)p = o; }
;     __device__ __forceinline__ void row(const f32x4 (&a)[2][2], int row, int pn, int wc, int fq) const {
;     ...
;         } else if (pn < 4) {
;             const int head = (pn - 2) * 4 + wc;
;             f32x4 g[2][2]; float ss = 0.f;
; #pragma unroll
;             for (int bj = 0; bj < 2; ++bj)
; #pragma unroll
;                 for (int n = 0; n < 2; ++n)
; #pragma unroll
;                     for (int j = 0; j < 4; ++j) { const float t = gelu_tanh(a[bj][n][j]); g[bj][n][j] = t; ss += t * t; }
;             ss += __shfl_xor(ss, 16); ss += __shfl_xor(ss, 32);
;             const float rs = rsqrtf(ss * (1.f / 64.f) + EPS);
; #pragma unroll
;             for (int bj = 0; bj < 2; ++bj) { const int d = head * 64 + bj * 32 + 8 * fq;
;                 const f32x4 v0 = g[bj][0] * rs * *(const f32x4*)(g_v + d), v1 = g[bj][1] * rs * *(const f32x4*)(g_v + d + 4);
;                 st_bf16x8(pV + (size_t)row * 512 + d, v0, v1);
;                 if (row >= NP && row < NTOK) { float* o = out + O_VS + (size_t)(row - NP) * 512 + d; *(f32x4*)o = v0; *(f32x4*)(o + 4) = v1; } }
.Lv_2:
	s_andn2_b64 vcc, exec, s[0:1]
	v_mov_b32_e32 v190, 0x3d372713
	v_mov_b32_e32 v192, 0xbfcc422a
	v_mov_b32_e32 v194, 0x3fb8aa3b
	v_pk_mul_f32 v[96:97], v[92:93], v[190:191] op_sel_hi:[1,0]
	v_pk_mul_f32 v[100:101], v[94:95], v[190:191] op_sel_hi:[1,0]
	v_pk_mul_f32 v[106:107], v[88:89], v[190:191] op_sel_hi:[1,0]
	v_pk_mul_f32 v[108:109], v[90:91], v[190:191] op_sel_hi:[1,0]
	v_pk_mul_f32 v[110:111], v[84:85], v[190:191] op_sel_hi:[1,0]
	v_pk_mul_f32 v[112:113], v[86:87], v[190:191] op_sel_hi:[1,0]
	v_pk_mul_f32 v[114:115], v[80:81], v[190:191] op_sel_hi:[1,0]
	v_pk_mul_f32 v[116:117], v[82:83], v[190:191] op_sel_hi:[1,0]
	v_pk_mul_f32 v[96:97], v[92:93], v[96:97]
	v_pk_mul_f32 v[100:101], v[94:95], v[100:101]
	v_pk_mul_f32 v[106:107], v[88:89], v[106:107]
	v_pk_mul_f32 v[108:109], v[90:91], v[108:109]
	v_pk_mul_f32 v[110:111], v[84:85], v[110:111]
	v_pk_mul_f32 v[112:113], v[86:87], v[112:113]
	v_pk_mul_f32 v[114:115], v[80:81], v[114:115]
	v_pk_mul_f32 v[116:117], v[82:83], v[116:117]
	v_pk_fma_f32 v[96:97], v[92:93], v[96:97], v[92:93]
	v_pk_fma_f32 v[100:101], v[94:95], v[100:101], v[94:95]
	v_pk_fma_f32 v[106:107], v[88:89], v[106:107], v[88:89]
	v_pk_fma_f32 v[108:109], v[90:91], v[108:109], v[90:91]
	v_pk_fma_f32 v[110:111], v[84:85], v[110:111], v[84:85]
	v_pk_fma_f32 v[112:113], v[86:87], v[112:113], v[86:87]
	v_pk_fma_f32 v[114:115], v[80:81], v[114:115], v[80:81]
	v_pk_fma_f32 v[116:117], v[82:83], v[116:117], v[82:83]
	v_pk_mul_f32 v[96:97], v[96:97], v[192:193] op_sel_hi:[1,0]
	v_pk_mul_f32 v[100:101], v[100:101], v[192:193] op_sel_hi:[1,0]
	v_pk_mul_f32 v[106:107], v[106:107], v[192:193] op_sel_hi:[1,0]
	v_pk_mul_f32 v[108:109], v[108:109], v[192:193] op_sel_hi:[1,0]
	v_pk_mul_f32 v[110:111], v[110:111], v[192:193] op_sel_hi:[1,0]
	v_pk_mul_f32 v[112:113], v[112:113], v[192:193] op_sel_hi:[1,0]
	v_pk_mul_f32 v[114:115], v[114:115], v[192:193] op_sel_hi:[1,0]
	v_pk_mul_f32 v[116:117], v[116:117], v[192:193] op_sel_hi:[1,0]
	v_pk_mul_f32 v[96:97], v[96:97], v[194:195] op_sel_hi:[1,0]
	v_pk_mul_f32 v[100:101], v[100:101], v[194:195] op_sel_hi:[1,0]
	v_pk_mul_f32 v[106:107], v[106:107], v[194:195] op_sel_hi:[1,0]
	v_pk_mul_f32 v[108:109], v[108:109], v[194:195] op_sel_hi:[1,0]
	v_pk_mul_f32 v[110:111], v[110:111], v[194:195] op_sel_hi:[1,0]
	v_pk_mul_f32 v[112:113], v[112:113], v[194:195] op_sel_hi:[1,0]
	v_pk_mul_f32 v[114:115], v[114:115], v[194:195] op_sel_hi:[1,0]
	v_pk_mul_f32 v[116:117], v[116:117], v[194:195] op_sel_hi:[1,0]
	v_exp_f32_e32 v96, v96
	v_exp_f32_e32 v97, v97
	v_exp_f32_e32 v100, v100
	v_exp_f32_e32 v101, v101
	v_exp_f32_e32 v106, v106
	v_exp_f32_e32 v107, v107
	v_exp_f32_e32 v108, v108
	v_exp_f32_e32 v109, v109
	v_exp_f32_e32 v110, v110
	v_exp_f32_e32 v111, v111
	v_exp_f32_e32 v112, v112
	v_exp_f32_e32 v113, v113
	v_exp_f32_e32 v114, v114
	v_exp_f32_e32 v115, v115
	v_exp_f32_e32 v116, v116
	v_exp_f32_e32 v117, v117
	v_pk_add_f32 v[96:97], v[96:97], 1.0 op_sel_hi:[1,0]
	v_pk_add_f32 v[100:101], v[100:101], 1.0 op_sel_hi:[1,0]
	v_pk_add_f32 v[106:107], v[106:107], 1.0 op_sel_hi:[1,0]
	v_pk_add_f32 v[108:109], v[108:109], 1.0 op_sel_hi:[1,0]
	v_pk_add_f32 v[110:111], v[110:111], 1.0 op_sel_hi:[1,0]
	v_pk_add_f32 v[112:113], v[112:113], 1.0 op_sel_hi:[1,0]
	v_pk_add_f32 v[114:115], v[114:115], 1.0 op_sel_hi:[1,0]
	v_pk_add_f32 v[116:117], v[116:117], 1.0 op_sel_hi:[1,0]
	v_rcp_f32_e32 v96, v96
	v_rcp_f32_e32 v97, v97
	v_rcp_f32_e32 v100, v100
	v_rcp_f32_e32 v101, v101
	v_rcp_f32_e32 v106, v106
	v_rcp_f32_e32 v107, v107
	v_rcp_f32_e32 v108, v108
	v_rcp_f32_e32 v109, v109
	v_rcp_f32_e32 v110, v110
	v_rcp_f32_e32 v111, v111
	v_rcp_f32_e32 v112, v112
	v_rcp_f32_e32 v113, v113
	v_rcp_f32_e32 v114, v114
	v_rcp_f32_e32 v115, v115
	v_rcp_f32_e32 v116, v116
	v_rcp_f32_e32 v117, v117
	v_pk_mul_f32 v[96:97], v[92:93], v[96:97]
	v_pk_mul_f32 v[100:101], v[94:95], v[100:101]
	v_pk_mul_f32 v[106:107], v[88:89], v[106:107]
	v_pk_mul_f32 v[108:109], v[90:91], v[108:109]
	v_pk_mul_f32 v[110:111], v[84:85], v[110:111]
	v_pk_mul_f32 v[112:113], v[86:87], v[112:113]
	v_pk_mul_f32 v[114:115], v[80:81], v[114:115]
	v_pk_mul_f32 v[116:117], v[82:83], v[116:117]
	v_pk_mul_f32 v[98:99], v[96:97], v[96:97]
	v_pk_mul_f32 v[102:103], v[100:101], v[100:101]
	v_add_f32_e32 v98, v98, v99
	v_add_f32_e32 v98, v102, v98
	v_pk_mul_f32 v[118:119], v[106:107], v[106:107]
	v_add_f32_e32 v98, v103, v98
	v_add_f32_e32 v98, v118, v98
	v_pk_mul_f32 v[120:121], v[108:109], v[108:109]
	v_add_f32_e32 v98, v119, v98
	v_add_f32_e32 v98, v120, v98
	v_pk_mul_f32 v[122:123], v[110:111], v[110:111]
	v_add_f32_e32 v98, v121, v98
	v_add_f32_e32 v98, v98, v122
	v_pk_mul_f32 v[124:125], v[112:113], v[112:113]
	v_add_f32_e32 v98, v123, v98
	v_add_f32_e32 v98, v124, v98
	v_pk_mul_f32 v[126:127], v[114:115], v[114:115]
	v_add_f32_e32 v98, v125, v98
	v_add_f32_e32 v98, v126, v98
	v_pk_mul_f32 v[128:129], v[116:117], v[116:117]
	v_add_f32_e32 v98, v127, v98
	v_add_f32_e32 v98, v128, v98
	v_add_f32_e32 v98, v129, v98
	ds_bpermute_b32 v99, v229, v98
	v_lshl_add_u64 v[128:129], v[140:141], 2, s[18:19]
	v_ashrrev_i32_e32 v105, 31, v104
	v_lshlrev_b64 v[122:123], 10, v[104:105]
	v_lshlrev_b32_e32 v120, 9, v104
	s_waitcnt lgkmcnt(0)
	v_add_f32_e32 v98, v98, v99
	ds_bpermute_b32 v99, v230, v98
	v_mov_b32_e32 v121, v141
	v_cndmask_b32_e64 v105, 0, 1, s[10:11]
	v_cmp_ne_u32_e64 s[0:1], 1, v105
	s_waitcnt lgkmcnt(0)
	v_add_f32_e32 v98, v98, v99
	v_fmamk_f32 v98, v98, 0x3c800000, v188
	v_cmp_gt_f32_e32 vcc, s13, v98
	v_mul_f32_e32 v99, 0x4b800000, v98
	s_nop 0
	v_cndmask_b32_e32 v98, v98, v99, vcc
	v_rsq_f32_e32 v98, v98
	s_nop 0
	v_mul_f32_e32 v99, 0x45800000, v98
	v_cndmask_b32_e32 v118, v98, v99, vcc
	v_pk_mul_f32 v[124:125], v[96:97], v[118:119] op_sel_hi:[1,0]
	v_pk_mul_f32 v[126:127], v[100:101], v[118:119] op_sel_hi:[1,0]
	v_mov_b64_e32 v[96:97], v[208:209]
	v_mov_b64_e32 v[98:99], v[210:211]
	v_mov_b64_e32 v[100:101], v[204:205]
	v_mov_b64_e32 v[102:103], v[206:207]
	v_pk_mul_f32 v[106:107], v[106:107], v[118:119] op_sel_hi:[1,0]
	v_pk_mul_f32 v[108:109], v[108:109], v[118:119] op_sel_hi:[1,0]
	s_andn2_b64 vcc, exec, s[10:11]
	v_pk_mul_f32 v[96:97], v[96:97], v[106:107]
	v_lshl_add_u64 v[106:107], s[46:47], 0, v[122:123]
	v_pk_mul_f32 v[102:103], v[102:103], v[126:127]
	v_pk_mul_f32 v[100:101], v[100:101], v[124:125]
	v_pk_mul_f32 v[98:99], v[98:99], v[108:109]
	v_lshl_add_u64 v[106:107], v[140:141], 1, v[106:107]
	v_lshl_add_u64 v[108:109], v[120:121], 2, s[56:57]
	v_cvt_pk_bf16_f32 v122, v100, v101
	v_cvt_pk_bf16_f32 v123, v102, v103
	v_cvt_pk_bf16_f32 v124, v96, v97
	v_cvt_pk_bf16_f32 v125, v98, v99
	v_mov_b64_e32 v[196:197], v[122:123]
	v_mov_b64_e32 v[198:199], v[124:125]
	s_cbranch_vccnz .LBB0_258
	v_lshl_add_u64 v[120:121], v[140:141], 2, v[108:109]
	v_lshl_add_u64 v[122:123], v[120:121], 0, s[70:71]
	v_add_co_u32_e32 v120, vcc, 0x2108000, v120
	s_nop 1
	v_addc_co_u32_e32 v121, vcc, 0, v121, vcc
	global_store_dwordx4 v[120:121], v[100:103], off
	global_store_dwordx4 v[122:123], v[96:99], off offset:16

; __device__ __forceinline__ float gelu_tanh(float x) { const float u = 1.5957691216f * (x + 0.044715f * x * x * x); return x * __builtin_amdgcn_rcpf(1.f + __expf(-u)); }
; __device__ __forceinline__ void st_bf16x8(bf16_t* p, const f32x4 a, const f32x4 b) { uint4 o; o.x = cvt_pk_bf16(a[0], a[1]); o.y = cvt_pk_bf16(a[2], a[3]); o.z = cvt_pk_bf16(b[0], b[1]); o.w = cvt_pk_bf16(b[2], b[3]); *(uint4*)p = o; }
;     __device__ __forceinline__ void row(const f32x4 (&a)[2][2], int row, int pn, int wc, int fq) const {
;     ...
;             const int head = (pn - 2) * 4 + wc;
;             f32x4 g[2][2]; float ss = 0.f;
; #pragma unroll
;             for (int bj = 0; bj < 2; ++bj)
; #pragma unroll
;                 for (int n = 0; n < 2; ++n)
; #pragma unroll
;                     for (int j = 0; j < 4; ++j) { const float t = gelu_tanh(a[bj][n][j]); g[bj][n][j] = t; ss += t * t; }
;             ss += __shfl_xor(ss, 16); ss += __shfl_xor(ss, 32);
;             const float rs = rsqrtf(ss * (1.f / 64.f) + EPS);
; #pragma unroll
;             for (int bj = 0; bj < 2; ++bj) { const int d = head * 64 + bj * 32 + 8 * fq;
;                 const f32x4 v0 = g[bj][0] * rs * *(const f32x4*)(g_v + d), v1 = g[bj][1] * rs * *(const f32x4*)(g_v + d + 4);
;                 st_bf16x8(pV + (size_t)row * 512 + d, v0, v1);
;                 if (row >= NP && row < NTOK) { float* o = out + O_VS + (size_t)(row - NP) * 512 + d; *(f32x4*)o = v0; *(f32x4*)(o + 4) = v1; } }
.Lv_3:
	s_and_b64 vcc, exec, s[0:1]
	v_mov_b32_e32 v190, 0x3d372713
	v_mov_b32_e32 v192, 0xbfcc422a
	v_mov_b32_e32 v194, 0x3fb8aa3b
	v_pk_mul_f32 v[80:81], v[76:77], v[190:191] op_sel_hi:[1,0]
	v_pk_mul_f32 v[84:85], v[78:79], v[190:191] op_sel_hi:[1,0]
	v_pk_mul_f32 v[90:91], v[72:73], v[190:191] op_sel_hi:[1,0]
	v_pk_mul_f32 v[92:93], v[74:75], v[190:191] op_sel_hi:[1,0]
	v_pk_mul_f32 v[94:95], v[68:69], v[190:191] op_sel_hi:[1,0]
	v_pk_mul_f32 v[96:97], v[70:71], v[190:191] op_sel_hi:[1,0]
	v_pk_mul_f32 v[98:99], v[64:65], v[190:191] op_sel_hi:[1,0]
	v_pk_mul_f32 v[100:101], v[66:67], v[190:191] op_sel_hi:[1,0]
	v_pk_mul_f32 v[80:81], v[76:77], v[80:81]
	v_pk_mul_f32 v[84:85], v[78:79], v[84:85]
	v_pk_mul_f32 v[90:91], v[72:73], v[90:91]
	v_pk_mul_f32 v[92:93], v[74:75], v[92:93]
	v_pk_mul_f32 v[94:95], v[68:69], v[94:95]
	v_pk_mul_f32 v[96:97], v[70:71], v[96:97]
	v_pk_mul_f32 v[98:99], v[64:65], v[98:99]
	v_pk_mul_f32 v[100:101], v[66:67], v[100:101]
	v_pk_fma_f32 v[80:81], v[76:77], v[80:81], v[76:77]
	v_pk_fma_f32 v[84:85], v[78:79], v[84:85], v[78:79]
	v_pk_fma_f32 v[90:91], v[72:73], v[90:91], v[72:73]
	v_pk_fma_f32 v[92:93], v[74:75], v[92:93], v[74:75]
	v_pk_fma_f32 v[94:95], v[68:69], v[94:95], v[68:69]
	v_pk_fma_f32 v[96:97], v[70:71], v[96:97], v[70:71]
	v_pk_fma_f32 v[98:99], v[64:65], v[98:99], v[64:65]
	v_pk_fma_f32 v[100:101], v[66:67], v[100:101], v[66:67]
	v_pk_mul_f32 v[80:81], v[80:81], v[192:193] op_sel_hi:[1,0]
	v_pk_mul_f32 v[84:85], v[84:85], v[192:193] op_sel_hi:[1,0]
	v_pk_mul_f32 v[90:91], v[90:91], v[192:193] op_sel_hi:[1,0]
	v_pk_mul_f32 v[92:93], v[92:93], v[192:193] op_sel_hi:[1,0]
	v_pk_mul_f32 v[94:95], v[94:95], v[192:193] op_sel_hi:[1,0]
	v_pk_mul_f32 v[96:97], v[96:97], v[192:193] op_sel_hi:[1,0]
	v_pk_mul_f32 v[98:99], v[98:99], v[192:193] op_sel_hi:[1,0]
	v_pk_mul_f32 v[100:101], v[100:101], v[192:193] op_sel_hi:[1,0]
	v_pk_mul_f32 v[80:81], v[80:81], v[194:195] op_sel_hi:[1,0]
	v_pk_mul_f32 v[84:85], v[84:85], v[194:195] op_sel_hi:[1,0]
	v_pk_mul_f32 v[90:91], v[90:91], v[194:195] op_sel_hi:[1,0]
	v_pk_mul_f32 v[92:93], v[92:93], v[194:195] op_sel_hi:[1,0]
	v_pk_mul_f32 v[94:95], v[94:95], v[194:195] op_sel_hi:[1,0]
	v_pk_mul_f32 v[96:97], v[96:97], v[194:195] op_sel_hi:[1,0]
	v_pk_mul_f32 v[98:99], v[98:99], v[194:195] op_sel_hi:[1,0]
	v_pk_mul_f32 v[100:101], v[100:101], v[194:195] op_sel_hi:[1,0]
	v_exp_f32_e32 v80, v80
	v_exp_f32_e32 v81, v81
	v_exp_f32_e32 v84, v84
	v_exp_f32_e32 v85, v85
	v_exp_f32_e32 v90, v90
	v_exp_f32_e32 v91, v91
	v_exp_f32_e32 v92, v92
	v_exp_f32_e32 v93, v93
	v_exp_f32_e32 v94, v94
	v_exp_f32_e32 v95, v95
	v_exp_f32_e32 v96, v96
	v_exp_f32_e32 v97, v97
	v_exp_f32_e32 v98, v98
	v_exp_f32_e32 v99, v99
	v_exp_f32_e32 v100, v100
	v_exp_f32_e32 v101, v101
	v_pk_add_f32 v[80:81], v[80:81], 1.0 op_sel_hi:[1,0]
	v_pk_add_f32 v[84:85], v[84:85], 1.0 op_sel_hi:[1,0]
	v_pk_add_f32 v[90:91], v[90:91], 1.0 op_sel_hi:[1,0]
	v_pk_add_f32 v[92:93], v[92:93], 1.0 op_sel_hi:[1,0]
	v_pk_add_f32 v[94:95], v[94:95], 1.0 op_sel_hi:[1,0]
	v_pk_add_f32 v[96:97], v[96:97], 1.0 op_sel_hi:[1,0]
	v_pk_add_f32 v[98:99], v[98:99], 1.0 op_sel_hi:[1,0]
	v_pk_add_f32 v[100:101], v[100:101], 1.0 op_sel_hi:[1,0]
	v_rcp_f32_e32 v80, v80
	v_rcp_f32_e32 v81, v81
	v_rcp_f32_e32 v84, v84
	v_rcp_f32_e32 v85, v85
	v_rcp_f32_e32 v90, v90
	v_rcp_f32_e32 v91, v91
	v_rcp_f32_e32 v92, v92
	v_rcp_f32_e32 v93, v93
	v_rcp_f32_e32 v94, v94
	v_rcp_f32_e32 v95, v95
	v_rcp_f32_e32 v96, v96
	v_rcp_f32_e32 v97, v97
	v_rcp_f32_e32 v98, v98
	v_rcp_f32_e32 v99, v99
	v_rcp_f32_e32 v100, v100
	v_rcp_f32_e32 v101, v101
	v_pk_mul_f32 v[80:81], v[76:77], v[80:81]
	v_pk_mul_f32 v[84:85], v[78:79], v[84:85]
	v_pk_mul_f32 v[90:91], v[72:73], v[90:91]
	v_pk_mul_f32 v[92:93], v[74:75], v[92:93]
	v_pk_mul_f32 v[94:95], v[68:69], v[94:95]
	v_pk_mul_f32 v[96:97], v[70:71], v[96:97]
	v_pk_mul_f32 v[98:99], v[64:65], v[98:99]
	v_pk_mul_f32 v[100:101], v[66:67], v[100:101]
	v_pk_mul_f32 v[82:83], v[80:81], v[80:81]
	v_pk_mul_f32 v[86:87], v[84:85], v[84:85]
	v_add_f32_e32 v82, v82, v83
	v_add_f32_e32 v82, v86, v82
	v_pk_mul_f32 v[102:103], v[90:91], v[90:91]
	v_add_f32_e32 v82, v87, v82
	v_add_f32_e32 v82, v102, v82
	v_pk_mul_f32 v[104:105], v[92:93], v[92:93]
	v_add_f32_e32 v82, v103, v82
	v_add_f32_e32 v82, v104, v82
	v_pk_mul_f32 v[106:107], v[94:95], v[94:95]
	v_add_f32_e32 v82, v105, v82
	v_add_f32_e32 v82, v82, v106
	v_pk_mul_f32 v[108:109], v[96:97], v[96:97]
	v_add_f32_e32 v82, v107, v82
	v_add_f32_e32 v82, v108, v82
	v_pk_mul_f32 v[110:111], v[98:99], v[98:99]
	v_add_f32_e32 v82, v109, v82
	v_add_f32_e32 v82, v110, v82
	v_pk_mul_f32 v[112:113], v[100:101], v[100:101]
	v_add_f32_e32 v82, v111, v82
	v_add_f32_e32 v82, v112, v82
	v_add_f32_e32 v82, v113, v82
	ds_bpermute_b32 v83, v229, v82
	v_lshl_add_u64 v[112:113], v[140:141], 2, s[18:19]
	v_ashrrev_i32_e32 v89, 31, v88
	v_lshlrev_b64 v[106:107], 10, v[88:89]
	v_lshlrev_b32_e32 v104, 9, v88
	s_waitcnt lgkmcnt(0)
	v_add_f32_e32 v82, v82, v83
	ds_bpermute_b32 v83, v230, v82
	v_mov_b32_e32 v105, v141
	v_cndmask_b32_e64 v89, 0, 1, s[10:11]
	v_cmp_ne_u32_e64 s[0:1], 1, v89
	s_waitcnt lgkmcnt(0)
	v_add_f32_e32 v82, v82, v83
	v_fmamk_f32 v82, v82, 0x3c800000, v188
	v_cmp_gt_f32_e32 vcc, s13, v82
	v_mul_f32_e32 v83, 0x4b800000, v82
	s_nop 0
	v_cndmask_b32_e32 v82, v82, v83, vcc
	v_rsq_f32_e32 v82, v82
	s_nop 0
	v_mul_f32_e32 v83, 0x45800000, v82
	v_cndmask_b32_e32 v102, v82, v83, vcc
	v_pk_mul_f32 v[108:109], v[80:81], v[102:103] op_sel_hi:[1,0]
	v_pk_mul_f32 v[110:111], v[84:85], v[102:103] op_sel_hi:[1,0]
	v_mov_b64_e32 v[80:81], v[208:209]
	v_mov_b64_e32 v[82:83], v[210:211]
	v_mov_b64_e32 v[84:85], v[204:205]
	v_mov_b64_e32 v[86:87], v[206:207]
	v_pk_mul_f32 v[90:91], v[90:91], v[102:103] op_sel_hi:[1,0]
	v_pk_mul_f32 v[92:93], v[92:93], v[102:103] op_sel_hi:[1,0]
	s_andn2_b64 vcc, exec, s[10:11]
	v_pk_mul_f32 v[80:81], v[80:81], v[90:91]
	v_lshl_add_u64 v[90:91], s[46:47], 0, v[106:107]
	v_pk_mul_f32 v[86:87], v[86:87], v[110:111]
	v_pk_mul_f32 v[84:85], v[84:85], v[108:109]
	v_pk_mul_f32 v[82:83], v[82:83], v[92:93]
	v_lshl_add_u64 v[90:91], v[140:141], 1, v[90:91]
	v_lshl_add_u64 v[92:93], v[104:105], 2, s[56:57]
	v_cvt_pk_bf16_f32 v106, v84, v85
	v_cvt_pk_bf16_f32 v107, v86, v87
	v_cvt_pk_bf16_f32 v108, v80, v81
	v_cvt_pk_bf16_f32 v109, v82, v83
	v_mov_b64_e32 v[196:197], v[106:107]
	v_mov_b64_e32 v[198:199], v[108:109]
	s_cbranch_vccnz .LBB0_275
	v_lshl_add_u64 v[104:105], v[140:141], 2, v[92:93]
	v_lshl_add_u64 v[106:107], v[104:105], 0, s[70:71]
	v_add_co_u32_e32 v104, vcc, 0x2108000, v104
	s_nop 1
	v_addc_co_u32_e32 v105, vcc, 0, v105, vcc
	global_store_dwordx4 v[104:105], v[84:87], off
	global_store_dwordx4 v[106:107], v[80:83], off offset:16

; __device__ __forceinline__ float gelu_tanh(float x) { const float u = 1.5957691216f * (x + 0.044715f * x * x * x); return x * __builtin_amdgcn_rcpf(1.f + __expf(-u)); }
; __device__ __forceinline__ void st_bf16x8(bf16_t* p, const f32x4 a, const f32x4 b) { uint4 o; o.x = cvt_pk_bf16(a[0], a[1]); o.y = cvt_pk_bf16(a[2], a[3]); o.z = cvt_pk_bf16(b[0], b[1]); o.w = cvt_pk_bf16(b[2], b[3]); *(uint4*)p = o; }
;     __device__ __forceinline__ void row(const f32x4 (&a)[2][2], int row, int pn, int wc, int fq) const {
;     ...
;             const int head = (pn - 2) * 4 + wc;
;             f32x4 g[2][2]; float ss = 0.f;
; #pragma unroll
;             for (int bj = 0; bj < 2; ++bj)
; #pragma unroll
;                 for (int n = 0; n < 2; ++n)
; #pragma unroll
;                     for (int j = 0; j < 4; ++j) { const float t = gelu_tanh(a[bj][n][j]); g[bj][n][j] = t; ss += t * t; }
;             ss += __shfl_xor(ss, 16); ss += __shfl_xor(ss, 32);
;             const float rs = rsqrtf(ss * (1.f / 64.f) + EPS);
; #pragma unroll
;             for (int bj = 0; bj < 2; ++bj) { const int d = head * 64 + bj * 32 + 8 * fq;
;                 const f32x4 v0 = g[bj][0] * rs * *(const f32x4*)(g_v + d), v1 = g[bj][1] * rs * *(const f32x4*)(g_v + d + 4);
;                 st_bf16x8(pV + (size_t)row * 512 + d, v0, v1);
;                 if (row >= NP && row < NTOK) { float* o = out + O_VS + (size_t)(row - NP) * 512 + d; *(f32x4*)o = v0; *(f32x4*)(o + 4) = v1; } }
.Lv_4:
	s_andn2_b64 vcc, exec, s[0:1]
	v_mov_b32_e32 v190, 0x3d372713
	v_mov_b32_e32 v192, 0xbfcc422a
	v_mov_b32_e32 v194, 0x3fb8aa3b
	v_pk_mul_f32 v[64:65], v[60:61], v[190:191] op_sel_hi:[1,0]
	v_pk_mul_f32 v[68:69], v[62:63], v[190:191] op_sel_hi:[1,0]
	v_pk_mul_f32 v[74:75], v[56:57], v[190:191] op_sel_hi:[1,0]
	v_pk_mul_f32 v[76:77], v[58:59], v[190:191] op_sel_hi:[1,0]
	v_pk_mul_f32 v[78:79], v[52:53], v[190:191] op_sel_hi:[1,0]
	v_pk_mul_f32 v[80:81], v[54:55], v[190:191] op_sel_hi:[1,0]
	v_pk_mul_f32 v[82:83], v[48:49], v[190:191] op_sel_hi:[1,0]
	v_pk_mul_f32 v[84:85], v[50:51], v[190:191] op_sel_hi:[1,0]
	v_pk_mul_f32 v[64:65], v[60:61], v[64:65]
	v_pk_mul_f32 v[68:69], v[62:63], v[68:69]
	v_pk_mul_f32 v[74:75], v[56:57], v[74:75]
	v_pk_mul_f32 v[76:77], v[58:59], v[76:77]
	v_pk_mul_f32 v[78:79], v[52:53], v[78:79]
	v_pk_mul_f32 v[80:81], v[54:55], v[80:81]
	v_pk_mul_f32 v[82:83], v[48:49], v[82:83]
	v_pk_mul_f32 v[84:85], v[50:51], v[84:85]
	v_pk_fma_f32 v[64:65], v[60:61], v[64:65], v[60:61]
	v_pk_fma_f32 v[68:69], v[62:63], v[68:69], v[62:63]
	v_pk_fma_f32 v[74:75], v[56:57], v[74:75], v[56:57]
	v_pk_fma_f32 v[76:77], v[58:59], v[76:77], v[58:59]
	v_pk_fma_f32 v[78:79], v[52:53], v[78:79], v[52:53]
	v_pk_fma_f32 v[80:81], v[54:55], v[80:81], v[54:55]
	v_pk_fma_f32 v[82:83], v[48:49], v[82:83], v[48:49]
	v_pk_fma_f32 v[84:85], v[50:51], v[84:85], v[50:51]
	v_pk_mul_f32 v[64:65], v[64:65], v[192:193] op_sel_hi:[1,0]
	v_pk_mul_f32 v[68:69], v[68:69], v[192:193] op_sel_hi:[1,0]
	v_pk_mul_f32 v[74:75], v[74:75], v[192:193] op_sel_hi:[1,0]
	v_pk_mul_f32 v[76:77], v[76:77], v[192:193] op_sel_hi:[1,0]
	v_pk_mul_f32 v[78:79], v[78:79], v[192:193] op_sel_hi:[1,0]
	v_pk_mul_f32 v[80:81], v[80:81], v[192:193] op_sel_hi:[1,0]
	v_pk_mul_f32 v[82:83], v[82:83], v[192:193] op_sel_hi:[1,0]
	v_pk_mul_f32 v[84:85], v[84:85], v[192:193] op_sel_hi:[1,0]
	v_pk_mul_f32 v[64:65], v[64:65], v[194:195] op_sel_hi:[1,0]
	v_pk_mul_f32 v[68:69], v[68:69], v[194:195] op_sel_hi:[1,0]
	v_pk_mul_f32 v[74:75], v[74:75], v[194:195] op_sel_hi:[1,0]
	v_pk_mul_f32 v[76:77], v[76:77], v[194:195] op_sel_hi:[1,0]
	v_pk_mul_f32 v[78:79], v[78:79], v[194:195] op_sel_hi:[1,0]
	v_pk_mul_f32 v[80:81], v[80:81], v[194:195] op_sel_hi:[1,0]
	v_pk_mul_f32 v[82:83], v[82:83], v[194:195] op_sel_hi:[1,0]
	v_pk_mul_f32 v[84:85], v[84:85], v[194:195] op_sel_hi:[1,0]
	v_exp_f32_e32 v64, v64
	v_exp_f32_e32 v65, v65
	v_exp_f32_e32 v68, v68
	v_exp_f32_e32 v69, v69
	v_exp_f32_e32 v74, v74
	v_exp_f32_e32 v75, v75
	v_exp_f32_e32 v76, v76
	v_exp_f32_e32 v77, v77
	v_exp_f32_e32 v78, v78
	v_exp_f32_e32 v79, v79
	v_exp_f32_e32 v80, v80
	v_exp_f32_e32 v81, v81
	v_exp_f32_e32 v82, v82
	v_exp_f32_e32 v83, v83
	v_exp_f32_e32 v84, v84
	v_exp_f32_e32 v85, v85
	v_pk_add_f32 v[64:65], v[64:65], 1.0 op_sel_hi:[1,0]
	v_pk_add_f32 v[68:69], v[68:69], 1.0 op_sel_hi:[1,0]
	v_pk_add_f32 v[74:75], v[74:75], 1.0 op_sel_hi:[1,0]
	v_pk_add_f32 v[76:77], v[76:77], 1.0 op_sel_hi:[1,0]
	v_pk_add_f32 v[78:79], v[78:79], 1.0 op_sel_hi:[1,0]
	v_pk_add_f32 v[80:81], v[80:81], 1.0 op_sel_hi:[1,0]
	v_pk_add_f32 v[82:83], v[82:83], 1.0 op_sel_hi:[1,0]
	v_pk_add_f32 v[84:85], v[84:85], 1.0 op_sel_hi:[1,0]
	v_rcp_f32_e32 v64, v64
	v_rcp_f32_e32 v65, v65
	v_rcp_f32_e32 v68, v68
	v_rcp_f32_e32 v69, v69
	v_rcp_f32_e32 v74, v74
	v_rcp_f32_e32 v75, v75
	v_rcp_f32_e32 v76, v76
	v_rcp_f32_e32 v77, v77
	v_rcp_f32_e32 v78, v78
	v_rcp_f32_e32 v79, v79
	v_rcp_f32_e32 v80, v80
	v_rcp_f32_e32 v81, v81
	v_rcp_f32_e32 v82, v82
	v_rcp_f32_e32 v83, v83
	v_rcp_f32_e32 v84, v84
	v_rcp_f32_e32 v85, v85
	v_pk_mul_f32 v[64:65], v[60:61], v[64:65]
	v_pk_mul_f32 v[68:69], v[62:63], v[68:69]
	v_pk_mul_f32 v[74:75], v[56:57], v[74:75]
	v_pk_mul_f32 v[76:77], v[58:59], v[76:77]
	v_pk_mul_f32 v[78:79], v[52:53], v[78:79]
	v_pk_mul_f32 v[80:81], v[54:55], v[80:81]
	v_pk_mul_f32 v[82:83], v[48:49], v[82:83]
	v_pk_mul_f32 v[84:85], v[50:51], v[84:85]
	v_pk_mul_f32 v[66:67], v[64:65], v[64:65]
	v_pk_mul_f32 v[70:71], v[68:69], v[68:69]
	v_add_f32_e32 v66, v66, v67
	v_add_f32_e32 v66, v70, v66
	v_pk_mul_f32 v[86:87], v[74:75], v[74:75]
	v_add_f32_e32 v66, v71, v66
	v_add_f32_e32 v66, v86, v66
	v_pk_mul_f32 v[88:89], v[76:77], v[76:77]
	v_add_f32_e32 v66, v87, v66
	v_add_f32_e32 v66, v88, v66
	v_pk_mul_f32 v[90:91], v[78:79], v[78:79]
	v_add_f32_e32 v66, v89, v66
	v_add_f32_e32 v66, v66, v90
	v_pk_mul_f32 v[92:93], v[80:81], v[80:81]
	v_add_f32_e32 v66, v91, v66
	v_add_f32_e32 v66, v92, v66
	v_pk_mul_f32 v[94:95], v[82:83], v[82:83]
	v_add_f32_e32 v66, v93, v66
	v_add_f32_e32 v66, v94, v66
	v_pk_mul_f32 v[96:97], v[84:85], v[84:85]
	v_add_f32_e32 v66, v95, v66
	v_add_f32_e32 v66, v96, v66
	v_add_f32_e32 v66, v97, v66
	ds_bpermute_b32 v67, v229, v66
	v_lshl_add_u64 v[96:97], v[140:141], 2, s[18:19]
	v_ashrrev_i32_e32 v73, 31, v72
	v_lshlrev_b64 v[90:91], 10, v[72:73]
	v_lshlrev_b32_e32 v88, 9, v72
	s_waitcnt lgkmcnt(0)
	v_add_f32_e32 v66, v66, v67
	ds_bpermute_b32 v67, v230, v66
	v_mov_b32_e32 v89, v141
	s_waitcnt lgkmcnt(0)
	v_add_f32_e32 v66, v66, v67
	v_fmamk_f32 v66, v66, 0x3c800000, v188
	v_cmp_gt_f32_e32 vcc, s13, v66
	v_mul_f32_e32 v67, 0x4b800000, v66
	s_nop 0
	v_cndmask_b32_e32 v66, v66, v67, vcc
	v_rsq_f32_e32 v66, v66
	s_nop 0
	v_mul_f32_e32 v67, 0x45800000, v66
	v_cndmask_b32_e32 v86, v66, v67, vcc
	v_pk_mul_f32 v[92:93], v[64:65], v[86:87] op_sel_hi:[1,0]
	v_pk_mul_f32 v[94:95], v[68:69], v[86:87] op_sel_hi:[1,0]
	v_mov_b64_e32 v[64:65], v[208:209]
	v_mov_b64_e32 v[66:67], v[210:211]
	v_mov_b64_e32 v[68:69], v[204:205]
	v_mov_b64_e32 v[70:71], v[206:207]
	v_pk_mul_f32 v[74:75], v[74:75], v[86:87] op_sel_hi:[1,0]
	v_pk_mul_f32 v[76:77], v[76:77], v[86:87] op_sel_hi:[1,0]
	v_pk_mul_f32 v[64:65], v[64:65], v[74:75]
	v_lshl_add_u64 v[74:75], s[46:47], 0, v[90:91]
	v_pk_mul_f32 v[70:71], v[70:71], v[94:95]
	v_pk_mul_f32 v[68:69], v[68:69], v[92:93]
	v_pk_mul_f32 v[66:67], v[66:67], v[76:77]
	v_lshl_add_u64 v[76:77], v[140:141], 1, v[74:75]
	v_lshl_add_u64 v[74:75], v[88:89], 2, s[56:57]
	v_cvt_pk_bf16_f32 v90, v68, v69
	v_cvt_pk_bf16_f32 v91, v70, v71
	v_cvt_pk_bf16_f32 v92, v64, v65
	v_cvt_pk_bf16_f32 v93, v66, v67
	v_mov_b64_e32 v[196:197], v[90:91]
	v_mov_b64_e32 v[198:199], v[92:93]
	s_and_saveexec_b64 s[0:1], s[10:11]
	s_cbranch_execz .LBB0_298
	v_lshl_add_u64 v[88:89], v[140:141], 2, v[74:75]
	v_lshl_add_u64 v[90:91], v[88:89], 0, s[70:71]
	v_add_co_u32_e32 v88, vcc, 0x2108000, v88
	s_nop 1
	v_addc_co_u32_e32 v89, vcc, 0, v89, vcc
	global_store_dwordx4 v[88:89], v[68:71], off
	global_store_dwordx4 v[90:91], v[64:67], off offset:16

; __device__ __forceinline__ float gelu_tanh(float x) { const float u = 1.5957691216f * (x + 0.044715f * x * x * x); return x * __builtin_amdgcn_rcpf(1.f + __expf(-u)); }
; __device__ __forceinline__ void st_bf16x8(bf16_t* p, const f32x4 a, const f32x4 b) { uint4 o; o.x = cvt_pk_bf16(a[0], a[1]); o.y = cvt_pk_bf16(a[2], a[3]); o.z = cvt_pk_bf16(b[0], b[1]); o.w = cvt_pk_bf16(b[2], b[3]); *(uint4*)p = o; }
;     __device__ __forceinline__ void row(const f32x4 (&a)[2][2], int row, int pn, int wc, int fq) const {
;     ...
;             const int head = (pn - 2) * 4 + wc;
;             f32x4 g[2][2]; float ss = 0.f;
; #pragma unroll
;             for (int bj = 0; bj < 2; ++bj)
; #pragma unroll
;                 for (int n = 0; n < 2; ++n)
; #pragma unroll
;                     for (int j = 0; j < 4; ++j) { const float t = gelu_tanh(a[bj][n][j]); g[bj][n][j] = t; ss += t * t; }
;             ss += __shfl_xor(ss, 16); ss += __shfl_xor(ss, 32);
;             const float rs = rsqrtf(ss * (1.f / 64.f) + EPS);
; #pragma unroll
;             for (int bj = 0; bj < 2; ++bj) { const int d = head * 64 + bj * 32 + 8 * fq;
;                 const f32x4 v0 = g[bj][0] * rs * *(const f32x4*)(g_v + d), v1 = g[bj][1] * rs * *(const f32x4*)(g_v + d + 4);
;                 st_bf16x8(pV + (size_t)row * 512 + d, v0, v1);
;                 if (row >= NP && row < NTOK) { float* o = out + O_VS + (size_t)(row - NP) * 512 + d; *(f32x4*)o = v0; *(f32x4*)(o + 4) = v1; } }
.Lv_5:
	s_andn2_b64 vcc, exec, s[0:1]
	v_mov_b32_e32 v190, 0x3d372713
	v_mov_b32_e32 v192, 0xbfcc422a
	v_mov_b32_e32 v194, 0x3fb8aa3b
	v_pk_mul_f32 v[48:49], v[44:45], v[190:191] op_sel_hi:[1,0]
	v_pk_mul_f32 v[52:53], v[46:47], v[190:191] op_sel_hi:[1,0]
	v_pk_mul_f32 v[58:59], v[40:41], v[190:191] op_sel_hi:[1,0]
	v_pk_mul_f32 v[60:61], v[42:43], v[190:191] op_sel_hi:[1,0]
	v_pk_mul_f32 v[62:63], v[36:37], v[190:191] op_sel_hi:[1,0]
	v_pk_mul_f32 v[64:65], v[38:39], v[190:191] op_sel_hi:[1,0]
	v_pk_mul_f32 v[66:67], v[32:33], v[190:191] op_sel_hi:[1,0]
	v_pk_mul_f32 v[68:69], v[34:35], v[190:191] op_sel_hi:[1,0]
	v_pk_mul_f32 v[48:49], v[44:45], v[48:49]
	v_pk_mul_f32 v[52:53], v[46:47], v[52:53]
	v_pk_mul_f32 v[58:59], v[40:41], v[58:59]
	v_pk_mul_f32 v[60:61], v[42:43], v[60:61]
	v_pk_mul_f32 v[62:63], v[36:37], v[62:63]
	v_pk_mul_f32 v[64:65], v[38:39], v[64:65]
	v_pk_mul_f32 v[66:67], v[32:33], v[66:67]
	v_pk_mul_f32 v[68:69], v[34:35], v[68:69]
	v_pk_fma_f32 v[48:49], v[44:45], v[48:49], v[44:45]
	v_pk_fma_f32 v[52:53], v[46:47], v[52:53], v[46:47]
	v_pk_fma_f32 v[58:59], v[40:41], v[58:59], v[40:41]
	v_pk_fma_f32 v[60:61], v[42:43], v[60:61], v[42:43]
	v_pk_fma_f32 v[62:63], v[36:37], v[62:63], v[36:37]
	v_pk_fma_f32 v[64:65], v[38:39], v[64:65], v[38:39]
	v_pk_fma_f32 v[66:67], v[32:33], v[66:67], v[32:33]
	v_pk_fma_f32 v[68:69], v[34:35], v[68:69], v[34:35]
	v_pk_mul_f32 v[48:49], v[48:49], v[192:193] op_sel_hi:[1,0]
	v_pk_mul_f32 v[52:53], v[52:53], v[192:193] op_sel_hi:[1,0]
	v_pk_mul_f32 v[58:59], v[58:59], v[192:193] op_sel_hi:[1,0]
	v_pk_mul_f32 v[60:61], v[60:61], v[192:193] op_sel_hi:[1,0]
	v_pk_mul_f32 v[62:63], v[62:63], v[192:193] op_sel_hi:[1,0]
	v_pk_mul_f32 v[64:65], v[64:65], v[192:193] op_sel_hi:[1,0]
	v_pk_mul_f32 v[66:67], v[66:67], v[192:193] op_sel_hi:[1,0]
	v_pk_mul_f32 v[68:69], v[68:69], v[192:193] op_sel_hi:[1,0]
	v_pk_mul_f32 v[48:49], v[48:49], v[194:195] op_sel_hi:[1,0]
	v_pk_mul_f32 v[52:53], v[52:53], v[194:195] op_sel_hi:[1,0]
	v_pk_mul_f32 v[58:59], v[58:59], v[194:195] op_sel_hi:[1,0]
	v_pk_mul_f32 v[60:61], v[60:61], v[194:195] op_sel_hi:[1,0]
	v_pk_mul_f32 v[62:63], v[62:63], v[194:195] op_sel_hi:[1,0]
	v_pk_mul_f32 v[64:65], v[64:65], v[194:195] op_sel_hi:[1,0]
	v_pk_mul_f32 v[66:67], v[66:67], v[194:195] op_sel_hi:[1,0]
	v_pk_mul_f32 v[68:69], v[68:69], v[194:195] op_sel_hi:[1,0]
	v_exp_f32_e32 v48, v48
	v_exp_f32_e32 v49, v49
	v_exp_f32_e32 v52, v52
	v_exp_f32_e32 v53, v53
	v_exp_f32_e32 v58, v58
	v_exp_f32_e32 v59, v59
	v_exp_f32_e32 v60, v60
	v_exp_f32_e32 v61, v61
	v_exp_f32_e32 v62, v62
	v_exp_f32_e32 v63, v63
	v_exp_f32_e32 v64, v64
	v_exp_f32_e32 v65, v65
	v_exp_f32_e32 v66, v66
	v_exp_f32_e32 v67, v67
	v_exp_f32_e32 v68, v68
	v_exp_f32_e32 v69, v69
	v_pk_add_f32 v[48:49], v[48:49], 1.0 op_sel_hi:[1,0]
	v_pk_add_f32 v[52:53], v[52:53], 1.0 op_sel_hi:[1,0]
	v_pk_add_f32 v[58:59], v[58:59], 1.0 op_sel_hi:[1,0]
	v_pk_add_f32 v[60:61], v[60:61], 1.0 op_sel_hi:[1,0]
	v_pk_add_f32 v[62:63], v[62:63], 1.0 op_sel_hi:[1,0]
	v_pk_add_f32 v[64:65], v[64:65], 1.0 op_sel_hi:[1,0]
	v_pk_add_f32 v[66:67], v[66:67], 1.0 op_sel_hi:[1,0]
	v_pk_add_f32 v[68:69], v[68:69], 1.0 op_sel_hi:[1,0]
	v_rcp_f32_e32 v48, v48
	v_rcp_f32_e32 v49, v49
	v_rcp_f32_e32 v52, v52
	v_rcp_f32_e32 v53, v53
	v_rcp_f32_e32 v58, v58
	v_rcp_f32_e32 v59, v59
	v_rcp_f32_e32 v60, v60
	v_rcp_f32_e32 v61, v61
	v_rcp_f32_e32 v62, v62
	v_rcp_f32_e32 v63, v63
	v_rcp_f32_e32 v64, v64
	v_rcp_f32_e32 v65, v65
	v_rcp_f32_e32 v66, v66
	v_rcp_f32_e32 v67, v67
	v_rcp_f32_e32 v68, v68
	v_rcp_f32_e32 v69, v69
	v_pk_mul_f32 v[48:49], v[44:45], v[48:49]
	v_pk_mul_f32 v[52:53], v[46:47], v[52:53]
	v_pk_mul_f32 v[58:59], v[40:41], v[58:59]
	v_pk_mul_f32 v[60:61], v[42:43], v[60:61]
	v_pk_mul_f32 v[62:63], v[36:37], v[62:63]
	v_pk_mul_f32 v[64:65], v[38:39], v[64:65]
	v_pk_mul_f32 v[66:67], v[32:33], v[66:67]
	v_pk_mul_f32 v[68:69], v[34:35], v[68:69]
	v_pk_mul_f32 v[50:51], v[48:49], v[48:49]
	v_pk_mul_f32 v[54:55], v[52:53], v[52:53]
	v_add_f32_e32 v50, v50, v51
	v_add_f32_e32 v50, v54, v50
	v_pk_mul_f32 v[70:71], v[58:59], v[58:59]
	v_add_f32_e32 v50, v55, v50
	v_add_f32_e32 v50, v70, v50
	v_pk_mul_f32 v[74:75], v[60:61], v[60:61]
	v_add_f32_e32 v50, v71, v50
	v_add_f32_e32 v50, v74, v50
	v_pk_mul_f32 v[76:77], v[62:63], v[62:63]
	v_add_f32_e32 v50, v75, v50
	v_add_f32_e32 v50, v50, v76
	v_pk_mul_f32 v[78:79], v[64:65], v[64:65]
	v_add_f32_e32 v50, v77, v50
	v_add_f32_e32 v50, v78, v50
	v_pk_mul_f32 v[80:81], v[66:67], v[66:67]
	v_add_f32_e32 v50, v79, v50
	v_add_f32_e32 v50, v80, v50
	v_pk_mul_f32 v[82:83], v[68:69], v[68:69]
	v_add_f32_e32 v50, v81, v50
	v_add_f32_e32 v50, v82, v50
	v_add_f32_e32 v50, v83, v50
	ds_bpermute_b32 v51, v229, v50
	v_lshl_add_u64 v[82:83], v[140:141], 2, s[18:19]
	v_ashrrev_i32_e32 v57, 31, v56
	v_lshlrev_b64 v[76:77], 10, v[56:57]
	v_lshlrev_b32_e32 v74, 9, v56
	s_waitcnt lgkmcnt(0)
	v_add_f32_e32 v50, v50, v51
	ds_bpermute_b32 v51, v230, v50
	v_mov_b32_e32 v75, v141
	s_waitcnt lgkmcnt(0)
	v_add_f32_e32 v50, v50, v51
	v_fmamk_f32 v50, v50, 0x3c800000, v188
	v_cmp_gt_f32_e32 vcc, s13, v50
	v_mul_f32_e32 v51, 0x4b800000, v50
	s_nop 0
	v_cndmask_b32_e32 v50, v50, v51, vcc
	v_rsq_f32_e32 v50, v50
	s_nop 0
	v_mul_f32_e32 v51, 0x45800000, v50
	v_cndmask_b32_e32 v70, v50, v51, vcc
	v_pk_mul_f32 v[78:79], v[48:49], v[70:71] op_sel_hi:[1,0]
	v_pk_mul_f32 v[80:81], v[52:53], v[70:71] op_sel_hi:[1,0]
	v_mov_b64_e32 v[48:49], v[208:209]
	v_mov_b64_e32 v[50:51], v[210:211]
	v_mov_b64_e32 v[52:53], v[204:205]
	v_mov_b64_e32 v[54:55], v[206:207]
	v_pk_mul_f32 v[58:59], v[58:59], v[70:71] op_sel_hi:[1,0]
	v_pk_mul_f32 v[60:61], v[60:61], v[70:71] op_sel_hi:[1,0]
	v_pk_mul_f32 v[48:49], v[48:49], v[58:59]
	v_lshl_add_u64 v[58:59], s[46:47], 0, v[76:77]
	v_pk_mul_f32 v[54:55], v[54:55], v[80:81]
	v_pk_mul_f32 v[52:53], v[52:53], v[78:79]
	v_pk_mul_f32 v[50:51], v[50:51], v[60:61]
	v_lshl_add_u64 v[60:61], v[140:141], 1, v[58:59]
	v_lshl_add_u64 v[58:59], v[74:75], 2, s[56:57]
	v_cvt_pk_bf16_f32 v76, v52, v53
	v_cvt_pk_bf16_f32 v77, v54, v55
	v_cvt_pk_bf16_f32 v78, v48, v49
	v_cvt_pk_bf16_f32 v79, v50, v51
	v_mov_b64_e32 v[196:197], v[76:77]
	v_mov_b64_e32 v[198:199], v[78:79]
	s_and_saveexec_b64 s[0:1], s[10:11]
	s_cbranch_execz .LBB0_314
	v_lshl_add_u64 v[74:75], v[140:141], 2, v[58:59]
	v_lshl_add_u64 v[76:77], v[74:75], 0, s[70:71]
	v_add_co_u32_e32 v74, vcc, 0x2108000, v74
	s_nop 1
	v_addc_co_u32_e32 v75, vcc, 0, v75, vcc
	global_store_dwordx4 v[74:75], v[52:55], off
	global_store_dwordx4 v[76:77], v[48:51], off offset:16

; __device__ __forceinline__ float gelu_tanh(float x) { const float u = 1.5957691216f * (x + 0.044715f * x * x * x); return x * __builtin_amdgcn_rcpf(1.f + __expf(-u)); }
; __device__ __forceinline__ void st_bf16x8(bf16_t* p, const f32x4 a, const f32x4 b) { uint4 o; o.x = cvt_pk_bf16(a[0], a[1]); o.y = cvt_pk_bf16(a[2], a[3]); o.z = cvt_pk_bf16(b[0], b[1]); o.w = cvt_pk_bf16(b[2], b[3]); *(uint4*)p = o; }
;     __device__ __forceinline__ void row(const f32x4 (&a)[2][2], int row, int pn, int wc, int fq) const {
;     ...
;             const int head = (pn - 2) * 4 + wc;
;             f32x4 g[2][2]; float ss = 0.f;
; #pragma unroll
;             for (int bj = 0; bj < 2; ++bj)
; #pragma unroll
;                 for (int n = 0; n < 2; ++n)
; #pragma unroll
;                     for (int j = 0; j < 4; ++j) { const float t = gelu_tanh(a[bj][n][j]); g[bj][n][j] = t; ss += t * t; }
;             ss += __shfl_xor(ss, 16); ss += __shfl_xor(ss, 32);
;             const float rs = rsqrtf(ss * (1.f / 64.f) + EPS);
; #pragma unroll
;             for (int bj = 0; bj < 2; ++bj) { const int d = head * 64 + bj * 32 + 8 * fq;
;                 const f32x4 v0 = g[bj][0] * rs * *(const f32x4*)(g_v + d), v1 = g[bj][1] * rs * *(const f32x4*)(g_v + d + 4);
;                 st_bf16x8(pV + (size_t)row * 512 + d, v0, v1);
;                 if (row >= NP && row < NTOK) { float* o = out + O_VS + (size_t)(row - NP) * 512 + d; *(f32x4*)o = v0; *(f32x4*)(o + 4) = v1; } }
.Lv_6:
	s_andn2_b64 vcc, exec, s[0:1]
	v_mov_b32_e32 v190, 0x3d372713
	v_mov_b32_e32 v192, 0xbfcc422a
	v_mov_b32_e32 v194, 0x3fb8aa3b
	v_pk_mul_f32 v[32:33], v[28:29], v[190:191] op_sel_hi:[1,0]
	v_pk_mul_f32 v[36:37], v[30:31], v[190:191] op_sel_hi:[1,0]
	v_pk_mul_f32 v[42:43], v[24:25], v[190:191] op_sel_hi:[1,0]
	v_pk_mul_f32 v[44:45], v[26:27], v[190:191] op_sel_hi:[1,0]
	v_pk_mul_f32 v[46:47], v[20:21], v[190:191] op_sel_hi:[1,0]
	v_pk_mul_f32 v[48:49], v[22:23], v[190:191] op_sel_hi:[1,0]
	v_pk_mul_f32 v[50:51], v[16:17], v[190:191] op_sel_hi:[1,0]
	v_pk_mul_f32 v[52:53], v[18:19], v[190:191] op_sel_hi:[1,0]
	v_pk_mul_f32 v[32:33], v[28:29], v[32:33]
	v_pk_mul_f32 v[36:37], v[30:31], v[36:37]
	v_pk_mul_f32 v[42:43], v[24:25], v[42:43]
	v_pk_mul_f32 v[44:45], v[26:27], v[44:45]
	v_pk_mul_f32 v[46:47], v[20:21], v[46:47]
	v_pk_mul_f32 v[48:49], v[22:23], v[48:49]
	v_pk_mul_f32 v[50:51], v[16:17], v[50:51]
	v_pk_mul_f32 v[52:53], v[18:19], v[52:53]
	v_pk_fma_f32 v[32:33], v[28:29], v[32:33], v[28:29]
	v_pk_fma_f32 v[36:37], v[30:31], v[36:37], v[30:31]
	v_pk_fma_f32 v[42:43], v[24:25], v[42:43], v[24:25]
	v_pk_fma_f32 v[44:45], v[26:27], v[44:45], v[26:27]
	v_pk_fma_f32 v[46:47], v[20:21], v[46:47], v[20:21]
	v_pk_fma_f32 v[48:49], v[22:23], v[48:49], v[22:23]
	v_pk_fma_f32 v[50:51], v[16:17], v[50:51], v[16:17]
	v_pk_fma_f32 v[52:53], v[18:19], v[52:53], v[18:19]
	v_pk_mul_f32 v[32:33], v[32:33], v[192:193] op_sel_hi:[1,0]
	v_pk_mul_f32 v[36:37], v[36:37], v[192:193] op_sel_hi:[1,0]
	v_pk_mul_f32 v[42:43], v[42:43], v[192:193] op_sel_hi:[1,0]
	v_pk_mul_f32 v[44:45], v[44:45], v[192:193] op_sel_hi:[1,0]
	v_pk_mul_f32 v[46:47], v[46:47], v[192:193] op_sel_hi:[1,0]
	v_pk_mul_f32 v[48:49], v[48:49], v[192:193] op_sel_hi:[1,0]
	v_pk_mul_f32 v[50:51], v[50:51], v[192:193] op_sel_hi:[1,0]
	v_pk_mul_f32 v[52:53], v[52:53], v[192:193] op_sel_hi:[1,0]
	v_pk_mul_f32 v[32:33], v[32:33], v[194:195] op_sel_hi:[1,0]
	v_pk_mul_f32 v[36:37], v[36:37], v[194:195] op_sel_hi:[1,0]
	v_pk_mul_f32 v[42:43], v[42:43], v[194:195] op_sel_hi:[1,0]
	v_pk_mul_f32 v[44:45], v[44:45], v[194:195] op_sel_hi:[1,0]
	v_pk_mul_f32 v[46:47], v[46:47], v[194:195] op_sel_hi:[1,0]
	v_pk_mul_f32 v[48:49], v[48:49], v[194:195] op_sel_hi:[1,0]
	v_pk_mul_f32 v[50:51], v[50:51], v[194:195] op_sel_hi:[1,0]
	v_pk_mul_f32 v[52:53], v[52:53], v[194:195] op_sel_hi:[1,0]
	v_exp_f32_e32 v32, v32
	v_exp_f32_e32 v33, v33
	v_exp_f32_e32 v36, v36
	v_exp_f32_e32 v37, v37
	v_exp_f32_e32 v42, v42
	v_exp_f32_e32 v43, v43
	v_exp_f32_e32 v44, v44
	v_exp_f32_e32 v45, v45
	v_exp_f32_e32 v46, v46
	v_exp_f32_e32 v47, v47
	v_exp_f32_e32 v48, v48
	v_exp_f32_e32 v49, v49
	v_exp_f32_e32 v50, v50
	v_exp_f32_e32 v51, v51
	v_exp_f32_e32 v52, v52
	v_exp_f32_e32 v53, v53
	v_pk_add_f32 v[32:33], v[32:33], 1.0 op_sel_hi:[1,0]
	v_pk_add_f32 v[36:37], v[36:37], 1.0 op_sel_hi:[1,0]
	v_pk_add_f32 v[42:43], v[42:43], 1.0 op_sel_hi:[1,0]
	v_pk_add_f32 v[44:45], v[44:45], 1.0 op_sel_hi:[1,0]
	v_pk_add_f32 v[46:47], v[46:47], 1.0 op_sel_hi:[1,0]
	v_pk_add_f32 v[48:49], v[48:49], 1.0 op_sel_hi:[1,0]
	v_pk_add_f32 v[50:51], v[50:51], 1.0 op_sel_hi:[1,0]
	v_pk_add_f32 v[52:53], v[52:53], 1.0 op_sel_hi:[1,0]
	v_rcp_f32_e32 v32, v32
	v_rcp_f32_e32 v33, v33
	v_rcp_f32_e32 v36, v36
	v_rcp_f32_e32 v37, v37
	v_rcp_f32_e32 v42, v42
	v_rcp_f32_e32 v43, v43
	v_rcp_f32_e32 v44, v44
	v_rcp_f32_e32 v45, v45
	v_rcp_f32_e32 v46, v46
	v_rcp_f32_e32 v47, v47
	v_rcp_f32_e32 v48, v48
	v_rcp_f32_e32 v49, v49
	v_rcp_f32_e32 v50, v50
	v_rcp_f32_e32 v51, v51
	v_rcp_f32_e32 v52, v52
	v_rcp_f32_e32 v53, v53
	v_pk_mul_f32 v[32:33], v[28:29], v[32:33]
	v_pk_mul_f32 v[36:37], v[30:31], v[36:37]
	v_pk_mul_f32 v[42:43], v[24:25], v[42:43]
	v_pk_mul_f32 v[44:45], v[26:27], v[44:45]
	v_pk_mul_f32 v[46:47], v[20:21], v[46:47]
	v_pk_mul_f32 v[48:49], v[22:23], v[48:49]
	v_pk_mul_f32 v[50:51], v[16:17], v[50:51]
	v_pk_mul_f32 v[52:53], v[18:19], v[52:53]
	v_pk_mul_f32 v[34:35], v[32:33], v[32:33]
	v_pk_mul_f32 v[38:39], v[36:37], v[36:37]
	v_add_f32_e32 v34, v34, v35
	v_add_f32_e32 v34, v38, v34
	v_pk_mul_f32 v[54:55], v[42:43], v[42:43]
	v_add_f32_e32 v34, v39, v34
	v_add_f32_e32 v34, v54, v34
	v_pk_mul_f32 v[56:57], v[44:45], v[44:45]
	v_add_f32_e32 v34, v55, v34
	v_add_f32_e32 v34, v56, v34
	v_pk_mul_f32 v[58:59], v[46:47], v[46:47]
	v_add_f32_e32 v34, v57, v34
	v_add_f32_e32 v34, v34, v58
	v_pk_mul_f32 v[60:61], v[48:49], v[48:49]
	v_add_f32_e32 v34, v59, v34
	v_add_f32_e32 v34, v60, v34
	v_pk_mul_f32 v[62:63], v[50:51], v[50:51]
	v_add_f32_e32 v34, v61, v34
	v_add_f32_e32 v34, v62, v34
	v_pk_mul_f32 v[64:65], v[52:53], v[52:53]
	v_add_f32_e32 v34, v63, v34
	v_add_f32_e32 v34, v64, v34
	v_add_f32_e32 v34, v65, v34
	ds_bpermute_b32 v35, v229, v34
	v_lshl_add_u64 v[64:65], v[140:141], 2, s[18:19]
	v_ashrrev_i32_e32 v41, 31, v40
	v_lshlrev_b64 v[58:59], 10, v[40:41]
	v_lshlrev_b32_e32 v56, 9, v40
	s_waitcnt lgkmcnt(0)
	v_add_f32_e32 v34, v34, v35
	ds_bpermute_b32 v35, v230, v34
	v_mov_b32_e32 v57, v141
	s_waitcnt lgkmcnt(0)
	v_add_f32_e32 v34, v34, v35
	v_fmamk_f32 v34, v34, 0x3c800000, v188
	v_cmp_gt_f32_e32 vcc, s13, v34
	v_mul_f32_e32 v35, 0x4b800000, v34
	s_nop 0
	v_cndmask_b32_e32 v34, v34, v35, vcc
	v_rsq_f32_e32 v34, v34
	s_nop 0
	v_mul_f32_e32 v35, 0x45800000, v34
	v_cndmask_b32_e32 v54, v34, v35, vcc
	v_pk_mul_f32 v[60:61], v[32:33], v[54:55] op_sel_hi:[1,0]
	v_pk_mul_f32 v[62:63], v[36:37], v[54:55] op_sel_hi:[1,0]
	v_mov_b64_e32 v[32:33], v[208:209]
	v_mov_b64_e32 v[34:35], v[210:211]
	v_mov_b64_e32 v[36:37], v[204:205]
	v_mov_b64_e32 v[38:39], v[206:207]
	v_pk_mul_f32 v[42:43], v[42:43], v[54:55] op_sel_hi:[1,0]
	v_pk_mul_f32 v[44:45], v[44:45], v[54:55] op_sel_hi:[1,0]
	v_pk_mul_f32 v[32:33], v[32:33], v[42:43]
	v_lshl_add_u64 v[42:43], s[46:47], 0, v[58:59]
	v_pk_mul_f32 v[38:39], v[38:39], v[62:63]
	v_pk_mul_f32 v[36:37], v[36:37], v[60:61]
	v_pk_mul_f32 v[34:35], v[34:35], v[44:45]
	v_lshl_add_u64 v[44:45], v[140:141], 1, v[42:43]
	v_lshl_add_u64 v[42:43], v[56:57], 2, s[56:57]
	v_cvt_pk_bf16_f32 v58, v36, v37
	v_cvt_pk_bf16_f32 v59, v38, v39
	v_cvt_pk_bf16_f32 v60, v32, v33
	v_cvt_pk_bf16_f32 v61, v34, v35
	v_mov_b64_e32 v[196:197], v[58:59]
	v_mov_b64_e32 v[198:199], v[60:61]
	s_and_saveexec_b64 s[0:1], s[10:11]
	s_cbranch_execz .LBB0_330
	v_lshl_add_u64 v[56:57], v[140:141], 2, v[42:43]
	v_lshl_add_u64 v[58:59], v[56:57], 0, s[70:71]
	v_add_co_u32_e32 v56, vcc, 0x2108000, v56
	s_nop 1
	v_addc_co_u32_e32 v57, vcc, 0, v57, vcc
	global_store_dwordx4 v[56:57], v[36:39], off
	global_store_dwordx4 v[58:59], v[32:35], off offset:16

; __device__ __forceinline__ float gelu_tanh(float x) { const float u = 1.5957691216f * (x + 0.044715f * x * x * x); return x * __builtin_amdgcn_rcpf(1.f + __expf(-u)); }
; __device__ __forceinline__ void st_bf16x8(bf16_t* p, const f32x4 a, const f32x4 b) { uint4 o; o.x = cvt_pk_bf16(a[0], a[1]); o.y = cvt_pk_bf16(a[2], a[3]); o.z = cvt_pk_bf16(b[0], b[1]); o.w = cvt_pk_bf16(b[2], b[3]); *(uint4*)p = o; }
;     __device__ __forceinline__ void row(const f32x4 (&a)[2][2], int row, int pn, int wc, int fq) const {
;     ...
;             const int head = (pn - 2) * 4 + wc;
;             f32x4 g[2][2]; float ss = 0.f;
; #pragma unroll
;             for (int bj = 0; bj < 2; ++bj)
; #pragma unroll
;                 for (int n = 0; n < 2; ++n)
; #pragma unroll
;                     for (int j = 0; j < 4; ++j) { const float t = gelu_tanh(a[bj][n][j]); g[bj][n][j] = t; ss += t * t; }
;             ss += __shfl_xor(ss, 16); ss += __shfl_xor(ss, 32);
;             const float rs = rsqrtf(ss * (1.f / 64.f) + EPS);
; #pragma unroll
;             for (int bj = 0; bj < 2; ++bj) { const int d = head * 64 + bj * 32 + 8 * fq;
;                 const f32x4 v0 = g[bj][0] * rs * *(const f32x4*)(g_v + d), v1 = g[bj][1] * rs * *(const f32x4*)(g_v + d + 4);
;                 st_bf16x8(pV + (size_t)row * 512 + d, v0, v1);
;                 if (row >= NP && row < NTOK) { float* o = out + O_VS + (size_t)(row - NP) * 512 + d; *(f32x4*)o = v0; *(f32x4*)(o + 4) = v1; } }
.Lv_7:
	s_and_b64 vcc, exec, s[0:1]
	v_mov_b32_e32 v190, 0x3d372713
	v_mov_b32_e32 v192, 0xbfcc422a
	v_mov_b32_e32 v194, 0x3fb8aa3b
	v_pk_mul_f32 v[16:17], v[12:13], v[190:191] op_sel_hi:[1,0]
	v_pk_mul_f32 v[20:21], v[14:15], v[190:191] op_sel_hi:[1,0]
	v_pk_mul_f32 v[26:27], v[8:9], v[190:191] op_sel_hi:[1,0]
	v_pk_mul_f32 v[28:29], v[10:11], v[190:191] op_sel_hi:[1,0]
	v_pk_mul_f32 v[30:31], v[4:5], v[190:191] op_sel_hi:[1,0]
	v_pk_mul_f32 v[32:33], v[6:7], v[190:191] op_sel_hi:[1,0]
	v_pk_mul_f32 v[34:35], v[0:1], v[190:191] op_sel_hi:[1,0]
	v_pk_mul_f32 v[36:37], v[2:3], v[190:191] op_sel_hi:[1,0]
	v_pk_mul_f32 v[16:17], v[12:13], v[16:17]
	v_pk_mul_f32 v[20:21], v[14:15], v[20:21]
	v_pk_mul_f32 v[26:27], v[8:9], v[26:27]
	v_pk_mul_f32 v[28:29], v[10:11], v[28:29]
	v_pk_mul_f32 v[30:31], v[4:5], v[30:31]
	v_pk_mul_f32 v[32:33], v[6:7], v[32:33]
	v_pk_mul_f32 v[34:35], v[0:1], v[34:35]
	v_pk_mul_f32 v[36:37], v[2:3], v[36:37]
	v_pk_fma_f32 v[16:17], v[12:13], v[16:17], v[12:13]
	v_pk_fma_f32 v[20:21], v[14:15], v[20:21], v[14:15]
	v_pk_fma_f32 v[26:27], v[8:9], v[26:27], v[8:9]
	v_pk_fma_f32 v[28:29], v[10:11], v[28:29], v[10:11]
	v_pk_fma_f32 v[30:31], v[4:5], v[30:31], v[4:5]
	v_pk_fma_f32 v[32:33], v[6:7], v[32:33], v[6:7]
	v_pk_fma_f32 v[34:35], v[0:1], v[34:35], v[0:1]
	v_pk_fma_f32 v[36:37], v[2:3], v[36:37], v[2:3]
	v_pk_mul_f32 v[16:17], v[16:17], v[192:193] op_sel_hi:[1,0]
	v_pk_mul_f32 v[20:21], v[20:21], v[192:193] op_sel_hi:[1,0]
	v_pk_mul_f32 v[26:27], v[26:27], v[192:193] op_sel_hi:[1,0]
	v_pk_mul_f32 v[28:29], v[28:29], v[192:193] op_sel_hi:[1,0]
	v_pk_mul_f32 v[30:31], v[30:31], v[192:193] op_sel_hi:[1,0]
	v_pk_mul_f32 v[32:33], v[32:33], v[192:193] op_sel_hi:[1,0]
	v_pk_mul_f32 v[34:35], v[34:35], v[192:193] op_sel_hi:[1,0]
	v_pk_mul_f32 v[36:37], v[36:37], v[192:193] op_sel_hi:[1,0]
	v_pk_mul_f32 v[16:17], v[16:17], v[194:195] op_sel_hi:[1,0]
	v_pk_mul_f32 v[20:21], v[20:21], v[194:195] op_sel_hi:[1,0]
	v_pk_mul_f32 v[26:27], v[26:27], v[194:195] op_sel_hi:[1,0]
	v_pk_mul_f32 v[28:29], v[28:29], v[194:195] op_sel_hi:[1,0]
	v_pk_mul_f32 v[30:31], v[30:31], v[194:195] op_sel_hi:[1,0]
	v_pk_mul_f32 v[32:33], v[32:33], v[194:195] op_sel_hi:[1,0]
	v_pk_mul_f32 v[34:35], v[34:35], v[194:195] op_sel_hi:[1,0]
	v_pk_mul_f32 v[36:37], v[36:37], v[194:195] op_sel_hi:[1,0]
	v_exp_f32_e32 v16, v16
	v_exp_f32_e32 v17, v17
	v_exp_f32_e32 v20, v20
	v_exp_f32_e32 v21, v21
	v_exp_f32_e32 v26, v26
	v_exp_f32_e32 v27, v27
	v_exp_f32_e32 v28, v28
	v_exp_f32_e32 v29, v29
	v_exp_f32_e32 v30, v30
	v_exp_f32_e32 v31, v31
	v_exp_f32_e32 v32, v32
	v_exp_f32_e32 v33, v33
	v_exp_f32_e32 v34, v34
	v_exp_f32_e32 v35, v35
	v_exp_f32_e32 v36, v36
	v_exp_f32_e32 v37, v37
	v_pk_add_f32 v[16:17], v[16:17], 1.0 op_sel_hi:[1,0]
	v_pk_add_f32 v[20:21], v[20:21], 1.0 op_sel_hi:[1,0]
	v_pk_add_f32 v[26:27], v[26:27], 1.0 op_sel_hi:[1,0]
	v_pk_add_f32 v[28:29], v[28:29], 1.0 op_sel_hi:[1,0]
	v_pk_add_f32 v[30:31], v[30:31], 1.0 op_sel_hi:[1,0]
	v_pk_add_f32 v[32:33], v[32:33], 1.0 op_sel_hi:[1,0]
	v_pk_add_f32 v[34:35], v[34:35], 1.0 op_sel_hi:[1,0]
	v_pk_add_f32 v[36:37], v[36:37], 1.0 op_sel_hi:[1,0]
	v_rcp_f32_e32 v16, v16
	v_rcp_f32_e32 v17, v17
	v_rcp_f32_e32 v20, v20
	v_rcp_f32_e32 v21, v21
	v_rcp_f32_e32 v26, v26
	v_rcp_f32_e32 v27, v27
	v_rcp_f32_e32 v28, v28
	v_rcp_f32_e32 v29, v29
	v_rcp_f32_e32 v30, v30
	v_rcp_f32_e32 v31, v31
	v_rcp_f32_e32 v32, v32
	v_rcp_f32_e32 v33, v33
	v_rcp_f32_e32 v34, v34
	v_rcp_f32_e32 v35, v35
	v_rcp_f32_e32 v36, v36
	v_rcp_f32_e32 v37, v37
	v_pk_mul_f32 v[16:17], v[12:13], v[16:17]
	v_pk_mul_f32 v[20:21], v[14:15], v[20:21]
	v_pk_mul_f32 v[26:27], v[8:9], v[26:27]
	v_pk_mul_f32 v[28:29], v[10:11], v[28:29]
	v_pk_mul_f32 v[30:31], v[4:5], v[30:31]
	v_pk_mul_f32 v[32:33], v[6:7], v[32:33]
	v_pk_mul_f32 v[34:35], v[0:1], v[34:35]
	v_pk_mul_f32 v[36:37], v[2:3], v[36:37]
	v_pk_mul_f32 v[18:19], v[16:17], v[16:17]
	v_pk_mul_f32 v[22:23], v[20:21], v[20:21]
	v_add_f32_e32 v18, v18, v19
	v_add_f32_e32 v18, v22, v18
	v_pk_mul_f32 v[38:39], v[26:27], v[26:27]
	v_add_f32_e32 v18, v23, v18
	v_add_f32_e32 v18, v38, v18
	v_pk_mul_f32 v[40:41], v[28:29], v[28:29]
	v_add_f32_e32 v18, v39, v18
	v_add_f32_e32 v18, v40, v18
	v_pk_mul_f32 v[42:43], v[30:31], v[30:31]
	v_add_f32_e32 v18, v41, v18
	v_add_f32_e32 v18, v18, v42
	v_pk_mul_f32 v[44:45], v[32:33], v[32:33]
	v_add_f32_e32 v18, v43, v18
	v_add_f32_e32 v18, v44, v18
	v_pk_mul_f32 v[46:47], v[34:35], v[34:35]
	v_add_f32_e32 v18, v45, v18
	v_add_f32_e32 v18, v46, v18
	v_pk_mul_f32 v[48:49], v[36:37], v[36:37]
	v_add_f32_e32 v18, v47, v18
	v_add_f32_e32 v18, v48, v18
	v_add_f32_e32 v18, v49, v18
	ds_bpermute_b32 v19, v229, v18
	v_lshl_add_u64 v[48:49], v[140:141], 2, s[18:19]
	v_ashrrev_i32_e32 v25, 31, v24
	v_lshlrev_b64 v[42:43], 10, v[24:25]
	v_lshlrev_b32_e32 v40, 9, v24
	s_waitcnt lgkmcnt(0)
	v_add_f32_e32 v18, v18, v19
	ds_bpermute_b32 v19, v230, v18
	v_mov_b32_e32 v41, v141
	s_waitcnt lgkmcnt(0)
	v_add_f32_e32 v18, v18, v19
	v_fmamk_f32 v18, v18, 0x3c800000, v188
	v_cmp_gt_f32_e32 vcc, s13, v18
	v_mul_f32_e32 v19, 0x4b800000, v18
	s_nop 0
	v_cndmask_b32_e32 v18, v18, v19, vcc
	v_rsq_f32_e32 v18, v18
	s_nop 0
	v_mul_f32_e32 v19, 0x45800000, v18
	v_cndmask_b32_e32 v38, v18, v19, vcc
	v_pk_mul_f32 v[44:45], v[16:17], v[38:39] op_sel_hi:[1,0]
	v_pk_mul_f32 v[46:47], v[20:21], v[38:39] op_sel_hi:[1,0]
	v_mov_b64_e32 v[16:17], v[208:209]
	v_mov_b64_e32 v[18:19], v[210:211]
	v_mov_b64_e32 v[20:21], v[204:205]
	v_mov_b64_e32 v[22:23], v[206:207]
	v_pk_mul_f32 v[26:27], v[26:27], v[38:39] op_sel_hi:[1,0]
	v_pk_mul_f32 v[28:29], v[28:29], v[38:39] op_sel_hi:[1,0]
	v_pk_mul_f32 v[16:17], v[16:17], v[26:27]
	v_lshl_add_u64 v[26:27], s[46:47], 0, v[42:43]
	v_pk_mul_f32 v[22:23], v[22:23], v[46:47]
	v_pk_mul_f32 v[20:21], v[20:21], v[44:45]
	v_pk_mul_f32 v[18:19], v[18:19], v[28:29]
	v_lshl_add_u64 v[28:29], v[140:141], 1, v[26:27]
	v_lshl_add_u64 v[26:27], v[40:41], 2, s[56:57]
	v_cvt_pk_bf16_f32 v42, v20, v21
	v_cvt_pk_bf16_f32 v43, v22, v23
	v_cvt_pk_bf16_f32 v44, v16, v17
	v_cvt_pk_bf16_f32 v45, v18, v19
	v_mov_b64_e32 v[196:197], v[42:43]
	v_mov_b64_e32 v[198:199], v[44:45]
	s_and_saveexec_b64 s[0:1], s[10:11]
	s_cbranch_execz .LBB0_348
	v_lshl_add_u64 v[40:41], v[140:141], 2, v[26:27]
	v_lshl_add_u64 v[42:43], v[40:41], 0, s[70:71]
	v_add_co_u32_e32 v40, vcc, 0x2108000, v40
	s_nop 1
	v_addc_co_u32_e32 v41, vcc, 0, v41, vcc
	global_store_dwordx4 v[40:41], v[20:23], off
	global_store_dwordx4 v[42:43], v[16:19], off offset:16
